# norm phases: gnorm/scale/shift vectors preloaded once per sequence, next row prefetched (P5,P10); P1 dwordx4 weight stream; S5 sample-tile partial loads batched
# speedup vs baseline: 1.0227x; 1.0213x over previous
.LBB0_244:
	s_load_dwordx2 s[8:9], s[0:1], 0x48
	s_add_u32 s23, s26, 0xde00000
	s_addc_u32 s30, s27, 0
	s_add_u32 s4, s26, 0xf000000
	s_addc_u32 s5, s27, 0
	s_cmpk_gt_i32 s12, 0x1fff
	s_cbranch_scc1 .LBB0_251
	s_load_dwordx2 s[6:7], s[0:1], 0x0
	s_ashr_i32 s13, s12, 31
	s_lshl_b64 s[14:15], s[12:13], 13
	v_mov_b32_e32 v3, 0
	v_lshlrev_b32_e32 v2, 4, v162
	s_waitcnt lgkmcnt(0)
	s_add_u32 s14, s6, s14
	s_addc_u32 s15, s7, s15
	v_lshl_add_u64 v[6:7], s[14:15], 0, v[2:3]
	s_movk_i32 s13, 0x1000
	v_add_co_u32_e32 v30, vcc, s13, v6
	global_load_dwordx4 v[62:65], v2, s[14:15] nt
	global_load_dwordx4 v[42:45], v2, s[14:15] offset:1024 nt
	global_load_dwordx4 v[26:29], v2, s[14:15] offset:2048 nt
	global_load_dwordx4 v[22:25], v2, s[14:15] offset:3072 nt
	v_addc_co_u32_e32 v31, vcc, 0, v7, vcc
	global_load_dwordx4 v[18:21], v[30:31], off nt
	global_load_dwordx4 v[14:17], v[30:31], off offset:1024 nt
	global_load_dwordx4 v[10:13], v[30:31], off offset:2048 nt
	global_load_dwordx4 v[6:9], v[30:31], off offset:3072 nt
	v_mbcnt_lo_u32_b32 v1, -1, 0
	v_mbcnt_hi_u32_b32 v5, -1, v1
	v_and_b32_e32 v1, 64, v5
	v_add_u32_e32 v30, 64, v1
	v_xor_b32_e32 v1, 1, v5
	v_cmp_lt_i32_e32 vcc, v1, v30
	v_xor_b32_e32 v31, 2, v5
	v_lshlrev_b32_e32 v4, 2, v162
	v_cndmask_b32_e32 v1, v5, v1, vcc
	v_cmp_lt_i32_e32 vcc, v31, v30
	v_or_b32_e32 v36, 0x400, v4
	s_lshl_b32 s13, s2, 10
	v_cndmask_b32_e32 v31, v5, v31, vcc
	v_lshlrev_b32_e32 v80, 2, v31
	v_xor_b32_e32 v31, 4, v5
	v_cmp_lt_i32_e32 vcc, v31, v30
	v_lshlrev_b32_e32 v38, 2, v36
	v_mov_b32_e32 v39, v3
	v_cndmask_b32_e32 v31, v5, v31, vcc
	v_lshlrev_b32_e32 v81, 2, v31
	v_xor_b32_e32 v31, 8, v5
	v_cmp_lt_i32_e32 vcc, v31, v30
	v_lshl_add_u64 v[76:77], s[6:7], 0, v[2:3]
	s_and_b32 s6, s2, 1
	v_cndmask_b32_e32 v31, v5, v31, vcc
	s_and_b32 s13, s13, 0x1800
	v_lshlrev_b32_e32 v82, 2, v31
	v_xor_b32_e32 v31, 16, v5
	v_lshl_add_u64 v[68:69], s[8:9], 0, v[38:39]
	v_or_b32_e32 v38, 0x500, v4
	s_lshl_b32 s6, s6, 10
	s_lshl_b32 s7, s2, 2
	v_cmp_lt_i32_e32 vcc, v31, v30
	v_lshlrev_b32_e32 v40, 2, v38
	v_mov_b32_e32 v41, v3
	s_or_b32 s6, s13, s6
	s_andn2_b32 s7, s7, 31
	s_lshl_b32 s14, s3, 2
	v_cndmask_b32_e32 v31, v5, v31, vcc
	v_lshl_add_u64 v[70:71], s[8:9], 0, v[40:41]
	v_or_b32_e32 v40, 0x600, v4
	s_add_i32 s6, s6, s7
	v_lshlrev_b32_e32 v83, 2, v31
	v_xor_b32_e32 v31, 32, v5
	v_lshlrev_b32_e32 v46, 2, v40
	v_mov_b32_e32 v47, v3
	s_or_b32 s6, s6, s14
	v_cmp_lt_i32_e32 vcc, v31, v30
	v_lshl_add_u64 v[72:73], s[8:9], 0, v[46:47]
	v_or_b32_e32 v46, 0x700, v4
	s_or_b32 s31, s6, 1
	s_or_b32 s6, s3, 8
	v_cndmask_b32_e32 v5, v5, v31, vcc
	v_lshl_add_u64 v[66:67], s[8:9], 0, v[2:3]
	v_or_b32_e32 v30, 0x100, v4
	v_or_b32_e32 v32, 0x200, v4
	v_or_b32_e32 v34, 0x300, v4
	v_lshlrev_b32_e32 v48, 2, v46
	v_mov_b32_e32 v49, v3
	v_lshlrev_b32_e32 v2, 3, v162
	s_mul_i32 s6, s20, s6
	s_mov_b32 s21, 0
	v_lshlrev_b32_e32 v1, 2, v1
	v_lshlrev_b32_e32 v84, 2, v5
	v_lshl_add_u64 v[74:75], s[8:9], 0, v[48:49]
	v_lshl_add_u64 v[78:79], s[4:5], 0, v[2:3]
	s_add_i32 s35, s2, s6
	v_mov_b32_e32 v85, 0x358637bd
	s_mov_b32 s36, 0xf800000
	v_mov_b32_e32 v86, 0x260
	v_lshlrev_b32_e32 v87, 2, v4
	v_lshlrev_b32_e32 v88, 2, v30
	v_lshlrev_b32_e32 v89, 2, v32
	v_lshlrev_b32_e32 v90, 2, v34
	v_lshlrev_b32_e32 v91, 2, v36
	v_lshlrev_b32_e32 v92, 2, v38
	v_lshlrev_b32_e32 v93, 2, v40
	v_lshlrev_b32_e32 v94, 2, v46
	v_mov_b32_e32 v2, v3
	v_mov_b32_e32 v4, v3
	v_mov_b32_e32 v5, v3
	v_mov_b32_e32 v30, v3
	v_mov_b32_e32 v31, v3
	v_mov_b32_e32 v32, v3
	v_mov_b32_e32 v33, v3
	v_mov_b32_e32 v34, v3
	v_mov_b32_e32 v35, v3
	v_mov_b32_e32 v36, v3
	v_mov_b32_e32 v37, v3
	v_mov_b32_e32 v38, v3
	v_mov_b32_e32 v40, v3
	v_mov_b32_e32 v46, v3
	v_mov_b32_e32 v48, v3
	v_mov_b32_e32 v50, v3
	v_mov_b32_e32 v51, v3
	v_mov_b32_e32 v52, v3
	v_mov_b32_e32 v53, v3
	v_mov_b32_e32 v54, v3
	v_mov_b32_e32 v55, v3
	v_mov_b32_e32 v56, v3
	v_mov_b32_e32 v57, v3
	v_mov_b32_e32 v58, v3
	v_mov_b32_e32 v59, v3
	v_mov_b32_e32 v60, v3
	v_mov_b32_e32 v61, v3
	s_mov_b32 s98, -1
	s_branch .LBB0_247
.LBB0_246:
	s_ashr_i32 s99, s12, 11
	s_cmp_eq_u32 s99, s98
	s_cbranch_scc1 .Lnorm_skip_246
	s_mov_b32 s98, s99
	s_ashr_i32 s6, s12, 11
	s_mul_hi_i32 s7, s6, 0x12000
	s_mul_i32 s6, s6, 0x12000
	s_add_u32 s18, s23, s6
	s_addc_u32 s19, s30, s7
	s_add_u32 s28, s18, 0x2000
	s_addc_u32 s29, s19, 0
	global_load_dwordx4 v[116:119], v[66:67], off
	global_load_dwordx4 v[120:123], v87, s[28:29]
	global_load_dwordx4 v[124:127], v87, s[18:19]
	global_load_dwordx4 v[128:131], v[66:67], off offset:1024
	global_load_dwordx4 v[132:135], v88, s[28:29]
	global_load_dwordx4 v[136:139], v87, s[18:19] offset:1024
	global_load_dwordx4 v[140:143], v[66:67], off offset:2048
	global_load_dwordx4 v[144:147], v89, s[28:29]
	global_load_dwordx4 v[164:167], v87, s[18:19] offset:2048
	global_load_dwordx4 v[168:171], v[66:67], off offset:3072
	global_load_dwordx4 v[172:175], v90, s[28:29]
	global_load_dwordx4 v[176:179], v87, s[18:19] offset:3072
	global_load_dwordx4 v[180:183], v[68:69], off
	global_load_dwordx4 v[184:187], v91, s[28:29]
	global_load_dwordx4 v[188:191], v91, s[18:19]
	global_load_dwordx4 v[192:195], v[70:71], off
	global_load_dwordx4 v[196:199], v92, s[28:29]
	global_load_dwordx4 v[200:203], v92, s[18:19]
	global_load_dwordx4 v[204:207], v[72:73], off
	global_load_dwordx4 v[208:211], v93, s[28:29]
	global_load_dwordx4 v[212:215], v93, s[18:19]
	global_load_dwordx4 v[216:219], v[74:75], off
	global_load_dwordx4 v[220:223], v94, s[28:29]
	global_load_dwordx4 v[224:227], v94, s[18:19]
.Lnorm_skip_246:
	s_waitcnt vmcnt(30)
	v_mov_b32_e32 v98, v43
	v_mov_b32_e32 v99, v63
	v_mov_b32_e32 v96, v42
	v_mov_b32_e32 v97, v62
	v_pk_mul_f32 v[98:99], v[98:99], v[98:99]
	v_mov_b32_e32 v100, v45
	v_mov_b32_e32 v101, v65
	v_pk_fma_f32 v[96:97], v[96:97], v[96:97], v[98:99]
	v_mov_b32_e32 v98, v44
	v_mov_b32_e32 v99, v64
	v_pk_mul_f32 v[100:101], v[100:101], v[100:101]
	s_ashr_i32 s6, s12, 11
	v_pk_fma_f32 v[98:99], v[98:99], v[98:99], v[100:101]
	s_waitcnt vmcnt(29)
	v_pk_mul_f32 v[100:101], v[26:27], v[26:27]
	v_pk_add_f32 v[96:97], v[96:97], v[98:99]
	v_pk_mul_f32 v[98:99], v[28:29], v[28:29]
	v_pk_add_f32 v[96:97], v[96:97], v[96:97] op_sel_hi:[0,1]
	v_pk_mov_b32 v[102:103], v[100:101], v[98:99] op_sel:[1,0]
	v_mov_b32_e32 v101, v99
	s_waitcnt vmcnt(28)
	v_mul_f32_e32 v96, v22, v22
	v_pk_add_f32 v[98:99], v[102:103], v[100:101]
	v_pk_fma_f32 v[100:101], v[22:23], v[22:23], v[96:97] op_sel_hi:[1,1,0]
	v_mul_f32_e32 v96, v24, v24
	v_pk_add_f32 v[98:99], v[98:99], v[98:99] op_sel_hi:[0,1]
	v_pk_fma_f32 v[102:103], v[24:25], v[24:25], v[96:97] op_sel_hi:[1,1,0]
	s_waitcnt vmcnt(27)
	v_mul_f32_e32 v100, v18, v18
	v_mul_f32_e32 v102, v19, v19
	v_mul_f32_e32 v98, v20, v20
	v_mul_f32_e32 v96, v21, v21
	v_pk_add_f32 v[100:101], v[100:101], v[102:103]
	v_pk_add_f32 v[96:97], v[98:99], v[96:97]
	s_waitcnt vmcnt(26)
	v_pk_mul_f32 v[98:99], v[16:17], v[16:17]
	v_pk_add_f32 v[96:97], v[100:101], v[96:97]
	v_pk_mul_f32 v[100:101], v[14:15], v[14:15]
	v_pk_add_f32 v[96:97], v[96:97], v[96:97] op_sel_hi:[0,1]
	v_pk_mov_b32 v[102:103], v[100:101], v[98:99] op_sel:[1,0]
	v_mov_b32_e32 v101, v99
	s_waitcnt vmcnt(25)
	v_mul_f32_e32 v96, v10, v10
	s_mul_hi_i32 s7, s6, 0x12000
	s_mul_i32 s6, s6, 0x12000
	v_pk_add_f32 v[98:99], v[102:103], v[100:101]
	v_pk_fma_f32 v[100:101], v[10:11], v[10:11], v[96:97] op_sel_hi:[1,1,0]
	v_mul_f32_e32 v96, v12, v12
	s_add_u32 s18, s23, s6
	v_pk_add_f32 v[98:99], v[98:99], v[98:99] op_sel_hi:[0,1]
	v_pk_fma_f32 v[102:103], v[12:13], v[12:13], v[96:97] op_sel_hi:[1,1,0]
	s_addc_u32 s19, s30, s7
	s_waitcnt vmcnt(24)
	v_mul_f32_e32 v100, v6, v6
	v_mul_f32_e32 v102, v7, v7
	v_mul_f32_e32 v98, v8, v8
	v_mul_f32_e32 v96, v9, v9
	v_pk_add_f32 v[100:101], v[100:101], v[102:103]
	v_pk_add_f32 v[96:97], v[98:99], v[96:97]
	s_add_u32 s28, s18, 0x2000
	v_pk_add_f32 v[96:97], v[100:101], v[96:97]
	s_addc_u32 s29, s19, 0
	v_add_f32_e32 v95, v96, v97
	s_waitcnt vmcnt(0)
	v_mov_b64_e32 v[96:97], v[116:117]
	v_mov_b64_e32 v[98:99], v[118:119]
	v_mov_b64_e32 v[100:101], v[120:121]
	v_mov_b64_e32 v[102:103], v[122:123]
	v_mov_b64_e32 v[104:105], v[124:125]
	v_mov_b64_e32 v[106:107], v[126:127]
	ds_bpermute_b32 v108, v1, v95
	s_ashr_i32 s13, s12, 31
	s_add_i32 s35, s35, s22
	s_add_i32 s21, s21, 1
	s_waitcnt lgkmcnt(0)
	v_add_f32_e32 v95, v95, v108
	ds_bpermute_b32 v108, v80, v95
	s_waitcnt lgkmcnt(0)
	v_add_f32_e32 v95, v95, v108
	ds_bpermute_b32 v108, v81, v95
	s_waitcnt lgkmcnt(0)
	v_add_f32_e32 v95, v95, v108
	ds_bpermute_b32 v108, v82, v95
	s_waitcnt lgkmcnt(0)
	v_add_f32_e32 v95, v95, v108
	ds_bpermute_b32 v108, v83, v95
	s_waitcnt lgkmcnt(0)
	v_add_f32_e32 v95, v95, v108
	ds_bpermute_b32 v108, v84, v95
	s_waitcnt lgkmcnt(0)
	v_add_f32_e32 v95, v95, v108
	v_fmamk_f32 v95, v95, 0x3a000000, v85
	v_mul_f32_e32 v108, 0x4f800000, v95
	v_cmp_gt_f32_e32 vcc, s36, v95
	s_nop 1
	v_cndmask_b32_e32 v95, v95, v108, vcc
	v_sqrt_f32_e32 v108, v95
	s_nop 0
	v_add_u32_e32 v109, -1, v108
	v_fma_f32 v110, -v109, v108, v95
	v_cmp_ge_f32_e64 s[6:7], 0, v110
	v_add_u32_e32 v110, 1, v108
	s_nop 0
	v_cndmask_b32_e64 v109, v108, v109, s[6:7]
	v_fma_f32 v108, -v110, v108, v95
	v_cmp_lt_f32_e64 s[6:7], 0, v108
	s_nop 1
	v_cndmask_b32_e64 v108, v109, v110, s[6:7]
	v_mul_f32_e32 v109, 0x37800000, v108
	v_cndmask_b32_e32 v108, v108, v109, vcc
	v_cmp_class_f32_e32 vcc, v95, v86
	s_nop 1
	v_cndmask_b32_e32 v95, v108, v95, vcc
	v_div_scale_f32 v108, s[6:7], v95, v95, 1.0
	v_rcp_f32_e32 v109, v108
	s_lshl_b64 s[6:7], s[12:13], 12
	s_mov_b32 s12, s14
	v_fma_f32 v110, -v108, v109, 1.0
	v_fmac_f32_e32 v109, v110, v109
	v_div_scale_f32 v110, vcc, 1.0, v95, 1.0
	v_mul_f32_e32 v111, v110, v109
	v_fma_f32 v112, -v108, v111, v110
	v_fmac_f32_e32 v111, v112, v109
	v_fma_f32 v108, -v108, v111, v110
	v_div_fmas_f32 v108, v108, v109, v111
	v_div_fixup_f32 v108, v108, v95, 1.0
	v_pk_mul_f32 v[64:65], v[64:65], v[108:109] op_sel_hi:[1,0]
	v_pk_mul_f32 v[62:63], v[62:63], v[108:109] op_sel_hi:[1,0]
	s_waitcnt vmcnt(0)
	v_pk_mul_f32 v[64:65], v[98:99], v[64:65]
	v_pk_mul_f32 v[62:63], v[96:97], v[62:63]
	v_pk_add_f32 v[96:97], v[102:103], 1.0 op_sel_hi:[1,0]
	v_pk_add_f32 v[98:99], v[100:101], 1.0 op_sel_hi:[1,0]
	v_pk_fma_f32 v[64:65], v[96:97], v[64:65], v[106:107]
	v_pk_fma_f32 v[62:63], v[98:99], v[62:63], v[104:105]
	v_lshl_add_u64 v[110:111], v[78:79], 0, s[6:7]
	v_cvt_pk_bf16_f32 v62, v62, v63
	v_cvt_pk_bf16_f32 v63, v64, v65
	global_store_dwordx2 v[110:111], v[62:63], off
	v_mov_b64_e32 v[62:63], v[128:129]
	v_mov_b64_e32 v[64:65], v[130:131]
	s_nop 0
	v_mov_b64_e32 v[96:97], v[132:133]
	v_mov_b64_e32 v[98:99], v[134:135]
	v_mov_b64_e32 v[100:101], v[136:137]
	v_mov_b64_e32 v[102:103], v[138:139]
	v_pk_mul_f32 v[44:45], v[44:45], v[108:109] op_sel_hi:[1,0]
	v_pk_mul_f32 v[42:43], v[42:43], v[108:109] op_sel_hi:[1,0]
	v_pk_mul_f32 v[28:29], v[28:29], v[108:109] op_sel_hi:[1,0]
	v_pk_mul_f32 v[26:27], v[26:27], v[108:109] op_sel_hi:[1,0]
	v_pk_mul_f32 v[24:25], v[24:25], v[108:109] op_sel_hi:[1,0]
	v_pk_mul_f32 v[22:23], v[22:23], v[108:109] op_sel_hi:[1,0]
	v_pk_mul_f32 v[20:21], v[20:21], v[108:109] op_sel_hi:[1,0]
	v_pk_mul_f32 v[18:19], v[18:19], v[108:109] op_sel_hi:[1,0]
	v_pk_mul_f32 v[16:17], v[16:17], v[108:109] op_sel_hi:[1,0]
	v_pk_mul_f32 v[14:15], v[14:15], v[108:109] op_sel_hi:[1,0]
	v_pk_mul_f32 v[12:13], v[12:13], v[108:109] op_sel_hi:[1,0]
	v_pk_mul_f32 v[10:11], v[10:11], v[108:109] op_sel_hi:[1,0]
	v_pk_mul_f32 v[112:113], v[8:9], v[108:109] op_sel_hi:[1,0]
	v_pk_mul_f32 v[108:109], v[6:7], v[108:109] op_sel_hi:[1,0]
	s_and_b64 vcc, exec, s[16:17]
	v_mov_b32_e32 v6, v58
	v_mov_b32_e32 v7, v59
	v_mov_b32_e32 v8, v60
	v_mov_b32_e32 v9, v61
	v_pk_mul_f32 v[42:43], v[62:63], v[42:43]
	v_pk_mul_f32 v[44:45], v[64:65], v[44:45]
	v_pk_add_f32 v[62:63], v[98:99], 1.0 op_sel_hi:[1,0]
	v_pk_add_f32 v[64:65], v[96:97], 1.0 op_sel_hi:[1,0]
	v_pk_fma_f32 v[44:45], v[62:63], v[44:45], v[102:103]
	v_pk_fma_f32 v[42:43], v[64:65], v[42:43], v[100:101]
	s_nop 0
	v_cvt_pk_bf16_f32 v42, v42, v43
	v_cvt_pk_bf16_f32 v43, v44, v45
	global_store_dwordx2 v[110:111], v[42:43], off offset:512
	v_mov_b64_e32 v[42:43], v[140:141]
	v_mov_b64_e32 v[44:45], v[142:143]
	s_nop 0
	v_mov_b64_e32 v[62:63], v[144:145]
	v_mov_b64_e32 v[64:65], v[146:147]
	v_mov_b64_e32 v[96:97], v[164:165]
	v_mov_b64_e32 v[98:99], v[166:167]
	v_pk_mul_f32 v[26:27], v[42:43], v[26:27]
	v_pk_mul_f32 v[28:29], v[44:45], v[28:29]
	v_pk_add_f32 v[42:43], v[64:65], 1.0 op_sel_hi:[1,0]
	v_pk_add_f32 v[44:45], v[62:63], 1.0 op_sel_hi:[1,0]
	v_pk_fma_f32 v[28:29], v[28:29], v[42:43], v[98:99]
	v_pk_fma_f32 v[26:27], v[26:27], v[44:45], v[96:97]
	s_nop 0
	v_cvt_pk_bf16_f32 v26, v26, v27
	v_cvt_pk_bf16_f32 v27, v28, v29
	global_store_dwordx2 v[110:111], v[26:27], off offset:1024
	v_mov_b64_e32 v[26:27], v[168:169]
	v_mov_b64_e32 v[28:29], v[170:171]
	s_nop 0
	v_mov_b64_e32 v[42:43], v[172:173]
	v_mov_b64_e32 v[44:45], v[174:175]
	v_mov_b64_e32 v[62:63], v[176:177]
	v_mov_b64_e32 v[64:65], v[178:179]
	v_pk_mul_f32 v[22:23], v[22:23], v[26:27]
	v_pk_mul_f32 v[24:25], v[24:25], v[28:29]
	v_pk_add_f32 v[26:27], v[44:45], 1.0 op_sel_hi:[1,0]
	v_pk_add_f32 v[28:29], v[42:43], 1.0 op_sel_hi:[1,0]
	v_pk_fma_f32 v[24:25], v[24:25], v[26:27], v[64:65]
	v_pk_fma_f32 v[22:23], v[22:23], v[28:29], v[62:63]
	v_mov_b32_e32 v62, v2
	v_cvt_pk_bf16_f32 v22, v22, v23
	v_cvt_pk_bf16_f32 v23, v24, v25
	global_store_dwordx2 v[110:111], v[22:23], off offset:1536
	v_mov_b64_e32 v[22:23], v[180:181]
	v_mov_b64_e32 v[24:25], v[182:183]
	s_nop 0
	v_mov_b64_e32 v[26:27], v[184:185]
	v_mov_b64_e32 v[28:29], v[186:187]
	v_mov_b64_e32 v[42:43], v[188:189]
	v_mov_b64_e32 v[44:45], v[190:191]
	v_mov_b32_e32 v63, v3
	v_mov_b32_e32 v64, v4
	v_mov_b32_e32 v65, v5
	v_pk_mul_f32 v[18:19], v[18:19], v[22:23]
	v_pk_mul_f32 v[20:21], v[20:21], v[24:25]
	v_pk_add_f32 v[22:23], v[28:29], 1.0 op_sel_hi:[1,0]
	v_pk_add_f32 v[24:25], v[26:27], 1.0 op_sel_hi:[1,0]
	v_pk_fma_f32 v[20:21], v[20:21], v[22:23], v[44:45]
	v_pk_fma_f32 v[18:19], v[18:19], v[24:25], v[42:43]
	v_mov_b32_e32 v42, v30
	v_cvt_pk_bf16_f32 v18, v18, v19
	v_cvt_pk_bf16_f32 v19, v20, v21
	global_store_dwordx2 v[110:111], v[18:19], off offset:2048
	v_mov_b64_e32 v[18:19], v[192:193]
	v_mov_b64_e32 v[20:21], v[194:195]
	s_nop 0
	v_mov_b64_e32 v[22:23], v[196:197]
	v_mov_b64_e32 v[24:25], v[198:199]
	v_mov_b64_e32 v[26:27], v[200:201]
	v_mov_b64_e32 v[28:29], v[202:203]
	v_mov_b32_e32 v43, v31
	v_mov_b32_e32 v44, v32
	v_mov_b32_e32 v45, v33
	v_pk_mul_f32 v[14:15], v[14:15], v[18:19]
	v_pk_mul_f32 v[16:17], v[16:17], v[20:21]
	v_pk_add_f32 v[18:19], v[24:25], 1.0 op_sel_hi:[1,0]
	v_pk_add_f32 v[20:21], v[22:23], 1.0 op_sel_hi:[1,0]
	v_pk_fma_f32 v[16:17], v[16:17], v[18:19], v[28:29]
	v_pk_fma_f32 v[14:15], v[14:15], v[20:21], v[26:27]
	v_mov_b32_e32 v26, v34
	v_cvt_pk_bf16_f32 v14, v14, v15
	v_cvt_pk_bf16_f32 v15, v16, v17
	global_store_dwordx2 v[110:111], v[14:15], off offset:2560
	v_mov_b64_e32 v[14:15], v[204:205]
	v_mov_b64_e32 v[16:17], v[206:207]
	s_nop 0
	v_mov_b64_e32 v[18:19], v[208:209]
	v_mov_b64_e32 v[20:21], v[210:211]
	v_mov_b64_e32 v[22:23], v[212:213]
	v_mov_b64_e32 v[24:25], v[214:215]
	v_mov_b32_e32 v27, v35
	v_mov_b32_e32 v28, v36
	v_mov_b32_e32 v29, v37
	v_pk_mul_f32 v[10:11], v[10:11], v[14:15]
	v_pk_mul_f32 v[12:13], v[12:13], v[16:17]
	v_pk_add_f32 v[14:15], v[20:21], 1.0 op_sel_hi:[1,0]
	v_pk_add_f32 v[16:17], v[18:19], 1.0 op_sel_hi:[1,0]
	v_pk_fma_f32 v[12:13], v[12:13], v[14:15], v[24:25]
	v_pk_fma_f32 v[10:11], v[10:11], v[16:17], v[22:23]
	v_mov_b32_e32 v14, v50
	v_cvt_pk_bf16_f32 v10, v10, v11
	v_cvt_pk_bf16_f32 v11, v12, v13
	global_store_dwordx2 v[110:111], v[10:11], off offset:3072
	v_mov_b64_e32 v[96:97], v[216:217]
	v_mov_b64_e32 v[98:99], v[218:219]
	v_mov_b64_e32 v[100:101], v[220:221]
	v_mov_b64_e32 v[102:103], v[222:223]
	v_mov_b64_e32 v[104:105], v[224:225]
	v_mov_b64_e32 v[106:107], v[226:227]
	v_mov_b32_e32 v10, v54
	v_mov_b32_e32 v11, v55
	v_mov_b32_e32 v12, v56
	v_mov_b32_e32 v13, v57
	v_mov_b32_e32 v15, v51
	v_mov_b32_e32 v16, v52
	v_mov_b32_e32 v17, v53
	v_mov_b32_e32 v18, v46
	v_mov_b32_e32 v19, v47
	v_mov_b32_e32 v20, v48
	v_mov_b32_e32 v21, v49
	v_mov_b32_e32 v22, v38
	v_mov_b32_e32 v23, v39
	v_mov_b32_e32 v24, v40
	v_mov_b32_e32 v25, v41
	v_pk_mul_f32 v[96:97], v[108:109], v[96:97]
	v_pk_mul_f32 v[98:99], v[112:113], v[98:99]
	v_pk_add_f32 v[102:103], v[102:103], 1.0 op_sel_hi:[1,0]
	v_pk_add_f32 v[100:101], v[100:101], 1.0 op_sel_hi:[1,0]
	v_pk_fma_f32 v[98:99], v[98:99], v[102:103], v[106:107]
	v_pk_fma_f32 v[96:97], v[96:97], v[100:101], v[104:105]
	s_nop 0
	v_cvt_pk_bf16_f32 v96, v96, v97
	v_cvt_pk_bf16_f32 v97, v98, v99
	global_store_dwordx2 v[110:111], v[96:97], off offset:3584
	s_cbranch_vccnz .LBB0_251

.LBB0_495:
	s_load_dwordx2 s[8:9], s[0:1], 0x68
	s_add_u32 s4, s26, 0xf000000
	s_addc_u32 s5, s27, 0
	s_cmpk_gt_i32 s12, 0x1fff
	s_cbranch_scc1 .LBB0_502
	s_ashr_i32 s13, s12, 31
	s_lshl_b64 s[6:7], s[12:13], 12
	s_add_u32 s6, s26, s6
	v_mov_b32_e32 v33, 0
	s_addc_u32 s7, s27, s7
	v_lshlrev_b32_e32 v32, 3, v162
	v_lshl_add_u64 v[2:3], s[6:7], 0, v[32:33]
	s_mov_b64 s[6:7], 0x16c00000
	v_lshl_add_u64 v[4:5], v[2:3], 0, s[6:7]
	global_load_dwordx2 v[6:7], v[4:5], off offset:512
	global_load_dwordx2 v[8:9], v[4:5], off offset:1024
	global_load_dwordx2 v[10:11], v[4:5], off offset:1536
	global_load_dwordx2 v[12:13], v[4:5], off offset:2048
	global_load_dwordx2 v[14:15], v[4:5], off offset:2560
	v_add_co_u32_e32 v2, vcc, 0x16c00000, v2
	global_load_dwordx2 v[16:17], v[4:5], off offset:3072
	s_nop 0
	v_addc_co_u32_e32 v3, vcc, 0, v3, vcc
	global_load_dwordx2 v[18:19], v[2:3], off
	global_load_dwordx2 v[20:21], v[4:5], off offset:3584
	v_mbcnt_lo_u32_b32 v1, -1, 0
	v_mbcnt_hi_u32_b32 v2, -1, v1
	v_and_b32_e32 v1, 64, v2
	v_xor_b32_e32 v3, 1, v2
	v_add_u32_e32 v26, 64, v1
	v_xor_b32_e32 v4, 2, v2
	v_cmp_lt_i32_e32 vcc, v3, v26
	v_xor_b32_e32 v5, 4, v2
	v_xor_b32_e32 v23, 8, v2
	v_cndmask_b32_e32 v1, v2, v3, vcc
	v_cmp_lt_i32_e32 vcc, v4, v26
	v_xor_b32_e32 v24, 16, v2
	v_xor_b32_e32 v25, 32, v2
	v_cndmask_b32_e32 v3, v2, v4, vcc
	v_cmp_lt_i32_e32 vcc, v5, v26
	v_lshlrev_b32_e32 v22, 2, v162
	v_lshlrev_b32_e32 v80, 2, v3
	v_cndmask_b32_e32 v4, v2, v5, vcc
	v_cmp_lt_i32_e32 vcc, v23, v26
	v_mov_b32_e32 v3, v33
	s_lshl_b32 s13, s2, 10
	v_cndmask_b32_e32 v5, v2, v23, vcc
	v_cmp_lt_i32_e32 vcc, v24, v26
	s_lshl_b32 s14, s3, 2
	s_and_b32 s13, s13, 0x1800
	v_cndmask_b32_e32 v23, v2, v24, vcc
	v_cmp_lt_i32_e32 vcc, v25, v26
	s_add_u32 s28, s26, 0xde06000
	s_addc_u32 s29, s27, 0
	v_cndmask_b32_e32 v2, v2, v25, vcc
	v_lshlrev_b32_e32 v84, 2, v2
	v_lshlrev_b32_e32 v2, 4, v162
	s_waitcnt lgkmcnt(0)
	v_lshl_add_u64 v[34:35], s[8:9], 0, v[2:3]
	s_mov_b32 s21, 0
	v_lshlrev_b32_e32 v1, 2, v1
	v_lshlrev_b32_e32 v81, 2, v4
	v_lshlrev_b32_e32 v82, 2, v5
	v_lshlrev_b32_e32 v83, 2, v23
	v_lshl_add_u64 v[46:47], s[4:5], 0, v[32:33]
	v_mov_b32_e32 v4, v33
	v_mov_b32_e32 v5, v33
	v_mov_b32_e32 v85, 0x358637bd
	s_mov_b32 s38, 0xf800000
	v_mov_b32_e32 v86, 0x260
	v_lshlrev_b32_e32 v87, 2, v22
	v_mov_b32_e32 v24, v33
	v_mov_b32_e32 v23, v33
	v_mov_b32_e32 v26, v33
	v_mov_b32_e32 v25, v33
	v_mov_b32_e32 v28, v33
	v_mov_b32_e32 v27, v33
	v_mov_b32_e32 v30, v33
	v_mov_b32_e32 v29, v33
	v_mov_b32_e32 v31, v33
	s_waitcnt vmcnt(7)
	v_lshlrev_b32_e32 v72, 16, v6
	s_waitcnt vmcnt(6)
	v_lshlrev_b32_e32 v68, 16, v8
	v_and_b32_e32 v69, 0xffff0000, v8
	s_waitcnt vmcnt(5)
	v_lshlrev_b32_e32 v64, 16, v10
	s_waitcnt vmcnt(3)
	v_lshlrev_b32_e32 v56, 16, v14
	v_and_b32_e32 v57, 0xffff0000, v14
	v_or_b32_e32 v14, 0x400, v22
	s_waitcnt vmcnt(2)
	v_lshlrev_b32_e32 v52, 16, v16
	v_and_b32_e32 v53, 0xffff0000, v16
	v_lshlrev_b32_e32 v2, 2, v14
	v_or_b32_e32 v16, 0x500, v22
	s_waitcnt vmcnt(1)
	v_lshlrev_b32_e32 v76, 16, v18
	v_and_b32_e32 v77, 0xffff0000, v18
	v_lshl_add_u64 v[36:37], s[8:9], 0, v[2:3]
	v_lshlrev_b32_e32 v2, 2, v16
	v_or_b32_e32 v18, 0x600, v22
	s_waitcnt vmcnt(0)
	v_lshlrev_b32_e32 v48, 16, v20
	v_and_b32_e32 v49, 0xffff0000, v20
	v_lshl_add_u64 v[38:39], s[8:9], 0, v[2:3]
	v_lshlrev_b32_e32 v2, 2, v18
	v_or_b32_e32 v20, 0x700, v22
	v_lshl_add_u64 v[40:41], s[8:9], 0, v[2:3]
	v_lshlrev_b32_e32 v2, 2, v20
	v_lshl_add_u64 v[42:43], s[8:9], 0, v[2:3]
	v_lshl_add_u64 v[2:3], s[26:27], 0, v[32:33]
	v_lshl_add_u64 v[44:45], v[2:3], 0, s[6:7]
	s_and_b32 s6, s2, 1
	s_lshl_b32 s6, s6, 10
	s_lshl_b32 s7, s2, 2
	s_or_b32 s6, s13, s6
	s_andn2_b32 s7, s7, 31
	s_add_i32 s6, s6, s7
	s_or_b32 s6, s6, s14
	s_or_b32 s30, s6, 1
	s_or_b32 s6, s3, 8
	v_and_b32_e32 v65, 0xffff0000, v10
	v_lshlrev_b32_e32 v60, 16, v12
	v_and_b32_e32 v61, 0xffff0000, v12
	v_or_b32_e32 v8, 0x100, v22
	v_or_b32_e32 v10, 0x200, v22
	v_or_b32_e32 v12, 0x300, v22
	s_mul_i32 s6, s20, s6
	v_and_b32_e32 v73, 0xffff0000, v6
	v_lshlrev_b32_e32 v74, 16, v7
	v_and_b32_e32 v75, 0xffff0000, v7
	v_lshlrev_b32_e32 v70, 16, v9
	v_and_b32_e32 v71, 0xffff0000, v9
	v_lshlrev_b32_e32 v66, 16, v11
	v_and_b32_e32 v67, 0xffff0000, v11
	v_lshlrev_b32_e32 v62, 16, v13
	v_and_b32_e32 v63, 0xffff0000, v13
	v_lshlrev_b32_e32 v58, 16, v15
	v_and_b32_e32 v59, 0xffff0000, v15
	v_lshlrev_b32_e32 v54, 16, v17
	v_and_b32_e32 v55, 0xffff0000, v17
	v_lshlrev_b32_e32 v78, 16, v19
	v_and_b32_e32 v79, 0xffff0000, v19
	v_lshlrev_b32_e32 v50, 16, v21
	v_and_b32_e32 v51, 0xffff0000, v21
	s_add_i32 s31, s2, s6
	v_mov_b32_e32 v2, v33
	v_mov_b32_e32 v3, v33
	v_mov_b32_e32 v6, v33
	v_lshlrev_b32_e32 v88, 2, v8
	v_lshlrev_b32_e32 v89, 2, v10
	v_lshlrev_b32_e32 v90, 2, v12
	v_lshlrev_b32_e32 v91, 2, v14
	v_lshlrev_b32_e32 v92, 2, v16
	v_lshlrev_b32_e32 v93, 2, v18
	v_lshlrev_b32_e32 v94, 2, v20
	v_mov_b32_e32 v8, v33
	v_mov_b32_e32 v7, v33
	v_mov_b32_e32 v10, v33
	v_mov_b32_e32 v9, v33
	v_mov_b32_e32 v12, v33
	v_mov_b32_e32 v11, v33
	v_mov_b32_e32 v14, v33
	v_mov_b32_e32 v13, v33
	v_mov_b32_e32 v16, v33
	v_mov_b32_e32 v15, v33
	v_mov_b32_e32 v18, v33
	v_mov_b32_e32 v17, v33
	v_mov_b32_e32 v20, v33
	v_mov_b32_e32 v19, v33
	v_mov_b32_e32 v22, v33
	v_mov_b32_e32 v21, v33
	v_mov_b32_e32 v32, v33
	s_mov_b32 s98, -1
	s_branch .LBB0_498
.LBB0_497:
	s_ashr_i32 s99, s12, 11
	s_cmp_eq_u32 s99, s98
	s_cbranch_scc1 .Lnorm_skip_497
	s_mov_b32 s98, s99
	s_ashr_i32 s6, s12, 11
	s_mul_hi_i32 s7, s6, 0x12000
	s_mul_i32 s6, s6, 0x12000
	s_add_u32 s6, s28, s6
	s_addc_u32 s7, s29, s7
	s_add_u32 s18, s6, 0x2000
	s_addc_u32 s19, s7, 0
	global_load_dwordx4 v[116:119], v[34:35], off
	global_load_dwordx4 v[120:123], v87, s[18:19]
	global_load_dwordx4 v[124:127], v87, s[6:7]
	global_load_dwordx4 v[128:131], v[34:35], off offset:1024
	global_load_dwordx4 v[132:135], v88, s[18:19]
	global_load_dwordx4 v[136:139], v87, s[6:7] offset:1024
	global_load_dwordx4 v[140:143], v[34:35], off offset:2048
	global_load_dwordx4 v[144:147], v89, s[18:19]
	global_load_dwordx4 v[164:167], v87, s[6:7] offset:2048
	global_load_dwordx4 v[168:171], v[34:35], off offset:3072
	global_load_dwordx4 v[172:175], v90, s[18:19]
	global_load_dwordx4 v[176:179], v87, s[6:7] offset:3072
	global_load_dwordx4 v[180:183], v[36:37], off
	global_load_dwordx4 v[184:187], v91, s[18:19]
	global_load_dwordx4 v[188:191], v91, s[6:7]
	global_load_dwordx4 v[192:195], v[38:39], off
	global_load_dwordx4 v[196:199], v92, s[18:19]
	global_load_dwordx4 v[200:203], v92, s[6:7]
	global_load_dwordx4 v[204:207], v[40:41], off
	global_load_dwordx4 v[208:211], v93, s[18:19]
	global_load_dwordx4 v[212:215], v93, s[6:7]
	global_load_dwordx4 v[216:219], v[42:43], off
	global_load_dwordx4 v[220:223], v94, s[18:19]
	global_load_dwordx4 v[224:227], v94, s[6:7]
.Lnorm_skip_497:
	s_and_b64 s[6:7], s[16:17], exec
	s_cselect_b32 s14, s12, s14
	s_ashr_i32 s15, s14, 31
	s_lshl_b64 s[6:7], s[14:15], 12
	v_lshl_add_u64 v[2:3], v[44:45], 0, s[6:7]
	global_load_dwordx2 v[4:5], v[2:3], off
	global_load_dwordx2 v[8:9], v[2:3], off offset:512
	global_load_dwordx2 v[12:13], v[2:3], off offset:1024
	global_load_dwordx2 v[16:17], v[2:3], off offset:1536
	global_load_dwordx2 v[20:21], v[2:3], off offset:2048
	global_load_dwordx2 v[24:25], v[2:3], off offset:2560
	global_load_dwordx2 v[28:29], v[2:3], off offset:3072
	global_load_dwordx2 v[148:149], v[2:3], off offset:3584
	v_mov_b32_e32 v98, v73
	v_mov_b32_e32 v99, v77
	v_mov_b32_e32 v96, v72
	v_mov_b32_e32 v97, v76
	v_pk_mul_f32 v[98:99], v[98:99], v[98:99]
	v_mov_b32_e32 v100, v75
	v_mov_b32_e32 v101, v79
	v_pk_fma_f32 v[96:97], v[96:97], v[96:97], v[98:99]
	v_mov_b32_e32 v98, v74
	v_mov_b32_e32 v99, v78
	v_pk_mul_f32 v[100:101], v[100:101], v[100:101]
	s_nop 0
	v_pk_fma_f32 v[98:99], v[98:99], v[98:99], v[100:101]
	v_pk_mul_f32 v[100:101], v[68:69], v[68:69]
	v_pk_add_f32 v[96:97], v[96:97], v[98:99]
	v_pk_mul_f32 v[98:99], v[70:71], v[70:71]
	v_pk_add_f32 v[96:97], v[96:97], v[96:97] op_sel_hi:[0,1]
	v_pk_mov_b32 v[102:103], v[100:101], v[98:99] op_sel:[1,0]
	v_mov_b32_e32 v101, v99
	v_pk_add_f32 v[98:99], v[102:103], v[100:101]
	v_mul_f32_e32 v100, v64, v64
	v_pk_fma_f32 v[100:101], v[64:65], v[64:65], v[100:101] op_sel_hi:[1,1,0]
	v_pk_add_f32 v[98:99], v[98:99], v[98:99] op_sel_hi:[0,1]
	v_mul_f32_e32 v100, v66, v66
	v_pk_fma_f32 v[102:103], v[66:67], v[66:67], v[100:101] op_sel_hi:[1,1,0]
	v_mul_f32_e32 v100, v60, v60
	v_mul_f32_e32 v102, v61, v61
	v_mul_f32_e32 v98, v62, v62
	v_mul_f32_e32 v96, v63, v63
	v_pk_add_f32 v[100:101], v[100:101], v[102:103]
	v_pk_add_f32 v[96:97], v[98:99], v[96:97]
	v_pk_mul_f32 v[98:99], v[58:59], v[58:59]
	v_pk_add_f32 v[96:97], v[100:101], v[96:97]
	v_pk_mul_f32 v[100:101], v[56:57], v[56:57]
	v_pk_add_f32 v[96:97], v[96:97], v[96:97] op_sel_hi:[0,1]
	v_pk_mov_b32 v[102:103], v[100:101], v[98:99] op_sel:[1,0]
	v_mov_b32_e32 v101, v99
	v_pk_add_f32 v[98:99], v[102:103], v[100:101]
	v_mul_f32_e32 v100, v52, v52
	v_pk_fma_f32 v[100:101], v[52:53], v[52:53], v[100:101] op_sel_hi:[1,1,0]
	v_pk_add_f32 v[98:99], v[98:99], v[98:99] op_sel_hi:[0,1]
	v_mul_f32_e32 v100, v54, v54
	v_pk_fma_f32 v[102:103], v[54:55], v[54:55], v[100:101] op_sel_hi:[1,1,0]
	v_mul_f32_e32 v100, v48, v48
	v_mul_f32_e32 v102, v49, v49
	v_mul_f32_e32 v98, v50, v50
	v_mul_f32_e32 v96, v51, v51
	v_pk_add_f32 v[100:101], v[100:101], v[102:103]
	v_pk_add_f32 v[96:97], v[98:99], v[96:97]
	s_nop 0
	v_pk_add_f32 v[96:97], v[100:101], v[96:97]
	s_nop 0
	v_add_f32_e32 v95, v96, v97
	ds_bpermute_b32 v96, v1, v95
	s_waitcnt lgkmcnt(0)
	v_add_f32_e32 v95, v95, v96
	ds_bpermute_b32 v96, v80, v95
	s_waitcnt lgkmcnt(0)
	v_add_f32_e32 v95, v95, v96
	ds_bpermute_b32 v96, v81, v95
	s_waitcnt lgkmcnt(0)
	v_add_f32_e32 v95, v95, v96
	ds_bpermute_b32 v96, v82, v95
	s_waitcnt lgkmcnt(0)
	v_add_f32_e32 v95, v95, v96
	ds_bpermute_b32 v96, v83, v95
	s_waitcnt lgkmcnt(0)
	v_add_f32_e32 v95, v95, v96
	ds_bpermute_b32 v96, v84, v95
	s_waitcnt lgkmcnt(0)
	v_add_f32_e32 v95, v95, v96
	v_fmamk_f32 v95, v95, 0x3a000000, v85
	v_mul_f32_e32 v96, 0x4f800000, v95
	v_cmp_gt_f32_e32 vcc, s38, v95
	s_nop 1
	v_cndmask_b32_e32 v95, v95, v96, vcc
	v_sqrt_f32_e32 v96, v95
	s_nop 0
	v_add_u32_e32 v97, -1, v96
	v_fma_f32 v98, -v97, v96, v95
	v_cmp_ge_f32_e64 s[6:7], 0, v98
	v_add_u32_e32 v98, 1, v96
	s_nop 0
	v_cndmask_b32_e64 v97, v96, v97, s[6:7]
	v_fma_f32 v96, -v98, v96, v95
	v_cmp_lt_f32_e64 s[6:7], 0, v96
	s_nop 1
	v_cndmask_b32_e64 v96, v97, v98, s[6:7]
	v_mul_f32_e32 v97, 0x37800000, v96
	v_cndmask_b32_e32 v96, v96, v97, vcc
	v_cmp_class_f32_e32 vcc, v95, v86
	s_nop 1
	v_cndmask_b32_e32 v95, v96, v95, vcc
	v_div_scale_f32 v96, s[6:7], v95, v95, 1.0
	v_rcp_f32_e32 v97, v96
	s_ashr_i32 s6, s12, 11
	s_mul_hi_i32 s7, s6, 0x12000
	s_mul_i32 s6, s6, 0x12000
	v_fma_f32 v98, -v96, v97, 1.0
	v_fmac_f32_e32 v97, v98, v97
	v_div_scale_f32 v98, vcc, 1.0, v95, 1.0
	v_mul_f32_e32 v99, v98, v97
	v_fma_f32 v100, -v96, v99, v98
	v_fmac_f32_e32 v99, v100, v97
	v_fma_f32 v96, -v96, v99, v98
	v_div_fmas_f32 v96, v96, v97, v99
	v_div_fixup_f32 v100, v96, v95, 1.0
	v_pk_mul_f32 v[96:97], v[78:79], v[100:101] op_sel_hi:[1,0]
	v_pk_mul_f32 v[98:99], v[76:77], v[100:101] op_sel_hi:[1,0]
	s_waitcnt vmcnt(8)
	v_mov_b64_e32 v[76:77], v[116:117]
	v_mov_b64_e32 v[78:79], v[118:119]
	s_add_u32 s6, s28, s6
	s_addc_u32 s7, s29, s7
	s_add_u32 s18, s6, 0x2000
	s_addc_u32 s19, s7, 0
	s_ashr_i32 s13, s12, 31
	s_lshl_b64 s[12:13], s[12:13], 12
	s_add_i32 s31, s31, s22
	s_add_i32 s21, s21, 1
	s_and_b64 vcc, exec, s[16:17]
	s_waitcnt vmcnt(8)
	v_pk_mul_f32 v[102:103], v[76:77], v[98:99]
	v_pk_mul_f32 v[104:105], v[78:79], v[96:97]
	v_mov_b64_e32 v[76:77], v[120:121]
	v_mov_b64_e32 v[78:79], v[122:123]
	v_mov_b64_e32 v[96:97], v[124:125]
	v_mov_b64_e32 v[98:99], v[126:127]
	v_pk_add_f32 v[78:79], v[78:79], 1.0 op_sel_hi:[1,0]
	v_pk_add_f32 v[76:77], v[76:77], 1.0 op_sel_hi:[1,0]
	v_pk_fma_f32 v[78:79], v[78:79], v[104:105], v[98:99]
	v_pk_fma_f32 v[76:77], v[76:77], v[102:103], v[96:97]
	v_lshl_add_u64 v[96:97], v[46:47], 0, s[12:13]
	v_cvt_pk_bf16_f32 v76, v76, v77
	v_cvt_pk_bf16_f32 v77, v78, v79
	global_store_dwordx2 v[96:97], v[76:77], off
	v_pk_mul_f32 v[76:77], v[74:75], v[100:101] op_sel_hi:[1,0]
	v_pk_mul_f32 v[78:79], v[72:73], v[100:101] op_sel_hi:[1,0]
	v_mov_b64_e32 v[72:73], v[128:129]
	v_mov_b64_e32 v[74:75], v[130:131]
	s_mov_b32 s12, s14
	v_pk_mul_f32 v[98:99], v[72:73], v[78:79]
	v_pk_mul_f32 v[102:103], v[74:75], v[76:77]
	v_mov_b64_e32 v[72:73], v[132:133]
	v_mov_b64_e32 v[74:75], v[134:135]
	v_mov_b64_e32 v[76:77], v[136:137]
	v_mov_b64_e32 v[78:79], v[138:139]
	v_pk_add_f32 v[74:75], v[74:75], 1.0 op_sel_hi:[1,0]
	v_pk_add_f32 v[72:73], v[72:73], 1.0 op_sel_hi:[1,0]
	v_pk_fma_f32 v[74:75], v[74:75], v[102:103], v[78:79]
	v_pk_fma_f32 v[72:73], v[72:73], v[98:99], v[76:77]
	s_nop 0
	v_cvt_pk_bf16_f32 v72, v72, v73
	v_cvt_pk_bf16_f32 v73, v74, v75
	global_store_dwordx2 v[96:97], v[72:73], off offset:512
	v_pk_mul_f32 v[72:73], v[70:71], v[100:101] op_sel_hi:[1,0]
	v_pk_mul_f32 v[74:75], v[68:69], v[100:101] op_sel_hi:[1,0]
	v_mov_b64_e32 v[68:69], v[140:141]
	v_mov_b64_e32 v[70:71], v[142:143]
	v_pk_mul_f32 v[76:77], v[68:69], v[74:75]
	v_pk_mul_f32 v[78:79], v[70:71], v[72:73]
	v_mov_b64_e32 v[68:69], v[144:145]
	v_mov_b64_e32 v[70:71], v[146:147]
	v_mov_b64_e32 v[72:73], v[164:165]
	v_mov_b64_e32 v[74:75], v[166:167]
	v_pk_add_f32 v[70:71], v[70:71], 1.0 op_sel_hi:[1,0]
	v_pk_add_f32 v[68:69], v[68:69], 1.0 op_sel_hi:[1,0]
	v_pk_fma_f32 v[70:71], v[78:79], v[70:71], v[74:75]
	v_pk_fma_f32 v[68:69], v[76:77], v[68:69], v[72:73]
	v_cvt_pk_bf16_f32 v68, v68, v69
	v_cvt_pk_bf16_f32 v69, v70, v71
	global_store_dwordx2 v[96:97], v[68:69], off offset:1024
	v_pk_mul_f32 v[68:69], v[66:67], v[100:101] op_sel_hi:[1,0]
	v_pk_mul_f32 v[70:71], v[64:65], v[100:101] op_sel_hi:[1,0]
	v_mov_b64_e32 v[64:65], v[168:169]
	v_mov_b64_e32 v[66:67], v[170:171]
	v_pk_mul_f32 v[72:73], v[70:71], v[64:65]
	v_pk_mul_f32 v[74:75], v[68:69], v[66:67]
	v_mov_b64_e32 v[64:65], v[172:173]
	v_mov_b64_e32 v[66:67], v[174:175]
	v_mov_b64_e32 v[68:69], v[176:177]
	v_mov_b64_e32 v[70:71], v[178:179]
	v_pk_add_f32 v[66:67], v[66:67], 1.0 op_sel_hi:[1,0]
	v_pk_add_f32 v[64:65], v[64:65], 1.0 op_sel_hi:[1,0]
	v_pk_fma_f32 v[66:67], v[74:75], v[66:67], v[70:71]
	v_pk_fma_f32 v[64:65], v[72:73], v[64:65], v[68:69]
	v_cvt_pk_bf16_f32 v64, v64, v65
	v_cvt_pk_bf16_f32 v65, v66, v67
	global_store_dwordx2 v[96:97], v[64:65], off offset:1536
	v_pk_mul_f32 v[64:65], v[62:63], v[100:101] op_sel_hi:[1,0]
	v_pk_mul_f32 v[66:67], v[60:61], v[100:101] op_sel_hi:[1,0]
	v_mov_b64_e32 v[60:61], v[180:181]
	v_mov_b64_e32 v[62:63], v[182:183]
	v_pk_mul_f32 v[68:69], v[66:67], v[60:61]
	v_pk_mul_f32 v[70:71], v[64:65], v[62:63]
	v_mov_b64_e32 v[60:61], v[184:185]
	v_mov_b64_e32 v[62:63], v[186:187]
	v_mov_b64_e32 v[64:65], v[188:189]
	v_mov_b64_e32 v[66:67], v[190:191]
	v_pk_add_f32 v[62:63], v[62:63], 1.0 op_sel_hi:[1,0]
	v_pk_add_f32 v[60:61], v[60:61], 1.0 op_sel_hi:[1,0]
	v_pk_fma_f32 v[62:63], v[70:71], v[62:63], v[66:67]
	v_pk_fma_f32 v[60:61], v[68:69], v[60:61], v[64:65]
	v_cvt_pk_bf16_f32 v60, v60, v61
	v_cvt_pk_bf16_f32 v61, v62, v63
	global_store_dwordx2 v[96:97], v[60:61], off offset:2048
	v_pk_mul_f32 v[60:61], v[58:59], v[100:101] op_sel_hi:[1,0]
	v_pk_mul_f32 v[62:63], v[56:57], v[100:101] op_sel_hi:[1,0]
	v_mov_b64_e32 v[56:57], v[192:193]
	v_mov_b64_e32 v[58:59], v[194:195]
	v_pk_mul_f32 v[64:65], v[62:63], v[56:57]
	v_pk_mul_f32 v[66:67], v[60:61], v[58:59]
	v_mov_b64_e32 v[56:57], v[196:197]
	v_mov_b64_e32 v[58:59], v[198:199]
	v_mov_b64_e32 v[60:61], v[200:201]
	v_mov_b64_e32 v[62:63], v[202:203]
	v_pk_add_f32 v[58:59], v[58:59], 1.0 op_sel_hi:[1,0]
	v_pk_add_f32 v[56:57], v[56:57], 1.0 op_sel_hi:[1,0]
	v_pk_fma_f32 v[58:59], v[66:67], v[58:59], v[62:63]
	v_pk_fma_f32 v[56:57], v[64:65], v[56:57], v[60:61]
	v_cvt_pk_bf16_f32 v56, v56, v57
	v_cvt_pk_bf16_f32 v57, v58, v59
	global_store_dwordx2 v[96:97], v[56:57], off offset:2560
	v_pk_mul_f32 v[56:57], v[54:55], v[100:101] op_sel_hi:[1,0]
	v_pk_mul_f32 v[58:59], v[52:53], v[100:101] op_sel_hi:[1,0]
	v_mov_b64_e32 v[52:53], v[204:205]
	v_mov_b64_e32 v[54:55], v[206:207]
	v_pk_mul_f32 v[60:61], v[58:59], v[52:53]
	v_pk_mul_f32 v[62:63], v[56:57], v[54:55]
	v_mov_b64_e32 v[52:53], v[208:209]
	v_mov_b64_e32 v[54:55], v[210:211]
	v_mov_b64_e32 v[56:57], v[212:213]
	v_mov_b64_e32 v[58:59], v[214:215]
	v_pk_add_f32 v[54:55], v[54:55], 1.0 op_sel_hi:[1,0]
	v_pk_add_f32 v[52:53], v[52:53], 1.0 op_sel_hi:[1,0]
	v_pk_fma_f32 v[54:55], v[62:63], v[54:55], v[58:59]
	v_pk_fma_f32 v[52:53], v[60:61], v[52:53], v[56:57]
	v_pk_mul_f32 v[58:59], v[48:49], v[100:101] op_sel_hi:[1,0]
	v_cvt_pk_bf16_f32 v48, v52, v53
	v_cvt_pk_bf16_f32 v49, v54, v55
	global_store_dwordx2 v[96:97], v[48:49], off offset:3072
	v_pk_mul_f32 v[56:57], v[50:51], v[100:101] op_sel_hi:[1,0]
	v_mov_b64_e32 v[48:49], v[216:217]
	v_mov_b64_e32 v[50:51], v[218:219]
	v_pk_mul_f32 v[58:59], v[58:59], v[48:49]
	v_pk_mul_f32 v[56:57], v[56:57], v[50:51]
	v_mov_b64_e32 v[48:49], v[220:221]
	v_mov_b64_e32 v[50:51], v[222:223]
	v_mov_b64_e32 v[52:53], v[224:225]
	v_mov_b64_e32 v[54:55], v[226:227]
	v_pk_add_f32 v[50:51], v[50:51], 1.0 op_sel_hi:[1,0]
	v_pk_add_f32 v[48:49], v[48:49], 1.0 op_sel_hi:[1,0]
	v_pk_fma_f32 v[50:51], v[56:57], v[50:51], v[54:55]
	v_pk_fma_f32 v[48:49], v[58:59], v[48:49], v[52:53]
	v_cvt_pk_bf16_f32 v48, v48, v49
	v_cvt_pk_bf16_f32 v49, v50, v51
	global_store_dwordx2 v[96:97], v[48:49], off offset:3584
	s_waitcnt vmcnt(8)
	v_lshlrev_b32_e32 v76, 16, v4
	v_and_b32_e32 v77, 0xffff0000, v4
	v_lshlrev_b32_e32 v78, 16, v5
	v_and_b32_e32 v79, 0xffff0000, v5
	v_lshlrev_b32_e32 v72, 16, v8
	v_and_b32_e32 v73, 0xffff0000, v8
	v_lshlrev_b32_e32 v74, 16, v9
	v_and_b32_e32 v75, 0xffff0000, v9
	v_lshlrev_b32_e32 v68, 16, v12
	v_and_b32_e32 v69, 0xffff0000, v12
	v_lshlrev_b32_e32 v70, 16, v13
	v_and_b32_e32 v71, 0xffff0000, v13
	v_lshlrev_b32_e32 v64, 16, v16
	v_and_b32_e32 v65, 0xffff0000, v16
	v_lshlrev_b32_e32 v66, 16, v17
	v_and_b32_e32 v67, 0xffff0000, v17
	v_lshlrev_b32_e32 v60, 16, v20
	v_and_b32_e32 v61, 0xffff0000, v20
	v_lshlrev_b32_e32 v62, 16, v21
	v_and_b32_e32 v63, 0xffff0000, v21
	v_lshlrev_b32_e32 v56, 16, v24
	v_and_b32_e32 v57, 0xffff0000, v24
	v_lshlrev_b32_e32 v58, 16, v25
	v_and_b32_e32 v59, 0xffff0000, v25
	v_lshlrev_b32_e32 v52, 16, v28
	v_and_b32_e32 v53, 0xffff0000, v28
	v_lshlrev_b32_e32 v54, 16, v29
	v_and_b32_e32 v55, 0xffff0000, v29
	v_lshlrev_b32_e32 v48, 16, v148
	v_and_b32_e32 v49, 0xffff0000, v148
	v_lshlrev_b32_e32 v50, 16, v149
	v_and_b32_e32 v51, 0xffff0000, v149
	s_cbranch_vccnz .LBB0_502

.LBB0_500:
	s_cmpk_gt_i32 s14, 0x1fff
	s_cselect_b64 s[16:17], -1, 0
	s_and_b64 vcc, exec, s[16:17]
	s_cbranch_vccnz .LBB0_497
	s_branch .LBB0_497

.LBB0_691:
	s_cmp_gt_u32 s39, 63
	s_cbranch_scc1 .LBB0_654
	s_mov_b32 s89, s7
	s_waitcnt vmcnt(13)
	v_lshl_add_u64 v[2:3], v[90:91], 0, s[88:89]
	s_mov_b32 s99, 0
	v_lshl_or_b32 v1, s80, 6, v162
	s_lshl_b32 s6, s81, 1
	v_readlane_b32 s8, v230, 15
	v_readlane_b32 s9, v230, 16
	global_load_dwordx4 v[220:223], v[2:3], off
	s_mov_b32 s98, 0x100000
	v_lshl_add_u64 v[4:5], v[2:3], 0, s[98:99]
	global_load_dwordx4 v[224:227], v[4:5], off
	s_mov_b32 s98, 0x200000
	v_lshl_add_u64 v[4:5], v[2:3], 0, s[98:99]
	global_load_dwordx4 v[232:235], v[4:5], off
	s_mov_b32 s98, 0x300000
	v_lshl_add_u64 v[4:5], v[2:3], 0, s[98:99]
	global_load_dwordx4 v[236:239], v[4:5], off
	s_mov_b32 s98, 0x400000
	v_lshl_add_u64 v[4:5], v[2:3], 0, s[98:99]
	global_load_dwordx4 v[240:243], v[4:5], off
	s_mov_b32 s98, 0x500000
	v_lshl_add_u64 v[4:5], v[2:3], 0, s[98:99]
	global_load_dwordx4 v[244:247], v[4:5], off
	s_mov_b32 s98, 0x600000
	v_lshl_add_u64 v[4:5], v[2:3], 0, s[98:99]
	global_load_dwordx4 v[248:251], v[4:5], off
	s_mov_b32 s98, 0x700000
	v_lshl_add_u64 v[4:5], v[2:3], 0, s[98:99]
	global_load_dwordx4 v[252:255], v[4:5], off
	s_waitcnt vmcnt(7)
	v_pk_add_f32 v[10:11], v[220:221], 0 op_sel_hi:[1,0]
	v_pk_add_f32 v[8:9], v[222:223], 0 op_sel_hi:[1,0]
	s_mov_b32 s98, 0x800000
	v_lshl_add_u64 v[4:5], v[2:3], 0, s[98:99]
	global_load_dwordx4 v[220:223], v[4:5], off
	s_waitcnt vmcnt(7)
	v_pk_add_f32 v[10:11], v[10:11], v[224:225]
	v_pk_add_f32 v[8:9], v[8:9], v[226:227]
	s_mov_b32 s98, 0x900000
	v_lshl_add_u64 v[4:5], v[2:3], 0, s[98:99]
	global_load_dwordx4 v[224:227], v[4:5], off
	s_waitcnt vmcnt(7)
	v_pk_add_f32 v[10:11], v[10:11], v[232:233]
	v_pk_add_f32 v[8:9], v[8:9], v[234:235]
	s_mov_b32 s98, 0xa00000
	v_lshl_add_u64 v[4:5], v[2:3], 0, s[98:99]
	global_load_dwordx4 v[232:235], v[4:5], off
	s_waitcnt vmcnt(7)
	v_pk_add_f32 v[10:11], v[10:11], v[236:237]
	v_pk_add_f32 v[8:9], v[8:9], v[238:239]
	s_mov_b32 s98, 0xb00000
	v_lshl_add_u64 v[4:5], v[2:3], 0, s[98:99]
	global_load_dwordx4 v[236:239], v[4:5], off
	s_waitcnt vmcnt(7)
	v_pk_add_f32 v[10:11], v[10:11], v[240:241]
	v_pk_add_f32 v[8:9], v[8:9], v[242:243]
	s_mov_b32 s98, 0xc00000
	v_lshl_add_u64 v[4:5], v[2:3], 0, s[98:99]
	global_load_dwordx4 v[240:243], v[4:5], off
	s_waitcnt vmcnt(7)
	v_pk_add_f32 v[10:11], v[10:11], v[244:245]
	v_pk_add_f32 v[8:9], v[8:9], v[246:247]
	s_mov_b32 s98, 0xd00000
	v_lshl_add_u64 v[4:5], v[2:3], 0, s[98:99]
	global_load_dwordx4 v[244:247], v[4:5], off
	s_waitcnt vmcnt(7)
	v_pk_add_f32 v[10:11], v[10:11], v[248:249]
	v_pk_add_f32 v[8:9], v[8:9], v[250:251]
	s_mov_b32 s98, 0xe00000
	v_lshl_add_u64 v[4:5], v[2:3], 0, s[98:99]
	global_load_dwordx4 v[248:251], v[4:5], off
	s_waitcnt vmcnt(7)
	v_pk_add_f32 v[10:11], v[10:11], v[252:253]
	v_pk_add_f32 v[8:9], v[8:9], v[254:255]
	s_mov_b32 s98, 0xf00000
	v_lshl_add_u64 v[4:5], v[2:3], 0, s[98:99]
	global_load_dwordx4 v[252:255], v[4:5], off
	s_waitcnt lgkmcnt(0)
	s_waitcnt vmcnt(7)
	v_pk_add_f32 v[10:11], v[10:11], v[220:221]
	v_pk_add_f32 v[8:9], v[8:9], v[222:223]
	s_waitcnt vmcnt(6)
	v_pk_add_f32 v[10:11], v[10:11], v[224:225]
	v_pk_add_f32 v[8:9], v[8:9], v[226:227]
	s_waitcnt vmcnt(5)
	v_pk_add_f32 v[10:11], v[10:11], v[232:233]
	v_pk_add_f32 v[8:9], v[8:9], v[234:235]
	s_waitcnt vmcnt(4)
	v_pk_add_f32 v[10:11], v[10:11], v[236:237]
	v_pk_add_f32 v[8:9], v[8:9], v[238:239]
	s_waitcnt vmcnt(3)
	v_pk_add_f32 v[10:11], v[10:11], v[240:241]
	v_pk_add_f32 v[8:9], v[8:9], v[242:243]
	s_waitcnt vmcnt(2)
	v_pk_add_f32 v[10:11], v[10:11], v[244:245]
	v_pk_add_f32 v[8:9], v[8:9], v[246:247]
	s_waitcnt vmcnt(1)
	v_pk_add_f32 v[10:11], v[10:11], v[248:249]
	v_pk_add_f32 v[8:9], v[8:9], v[250:251]
	s_waitcnt vmcnt(0)
	v_pk_add_f32 v[6:7], v[8:9], v[254:255]
	v_pk_add_f32 v[4:5], v[10:11], v[252:253]
	v_cvt_pk_bf16_f32 v45, v6, v7
	v_cvt_pk_bf16_f32 v44, v4, v5
	v_lshl_add_u64 v[2:3], v[92:93], 0, s[6:7]
	s_lshl_b32 s6, s80, 8
	v_mfma_f32_16x16x16_bf16 v[8:11], v[44:45], v[124:125], 0
	v_mfma_f32_16x16x16_bf16 v[12:15], v[44:45], v[68:69], 0
	s_nop 7
	ds_write2_b32 v153, v8, v12 offset1:16
	ds_write2_b32 v153, v9, v13 offset0:132 offset1:148
	ds_write2_b32 v17, v10, v14 offset0:8 offset1:24
	ds_write2_b32 v17, v11, v15 offset0:140 offset1:156
	v_mfma_f32_16x16x16_bf16 v[8:11], v[44:45], v[60:61], 0
	v_mfma_f32_16x16x16_bf16 v[12:15], v[44:45], v[52:53], 0
	s_nop 7
	ds_write2_b32 v153, v8, v12 offset0:32 offset1:48
	ds_write2_b32 v153, v9, v13 offset0:164 offset1:180
	ds_write2_b32 v17, v10, v14 offset0:40 offset1:56
	ds_write2_b32 v17, v11, v15 offset0:172 offset1:188
	v_mfma_f32_16x16x16_bf16 v[8:11], v[44:45], v[66:67], 0
	v_mfma_f32_16x16x16_bf16 v[12:15], v[44:45], v[58:59], 0
	s_nop 7
	ds_write2_b32 v153, v8, v12 offset0:64 offset1:80
	ds_write2_b32 v153, v9, v13 offset0:196 offset1:212
	ds_write2_b32 v17, v10, v14 offset0:72 offset1:88
	ds_write2_b32 v17, v11, v15 offset0:204 offset1:220
	v_mfma_f32_16x16x16_bf16 v[8:11], v[44:45], v[50:51], 0
	v_mfma_f32_16x16x16_bf16 v[12:15], v[44:45], v[42:43], 0
	s_nop 7
	ds_write2_b32 v153, v8, v12 offset0:96 offset1:112
	ds_write2_b32 v153, v9, v13 offset0:228 offset1:244
	ds_write2_b32 v17, v10, v14 offset0:104 offset1:120
	ds_write2_b32 v17, v11, v15 offset0:236 offset1:252
	v_or_b32_e32 v8, s48, v1
	v_mov_b32_e32 v9, s49
	v_lshlrev_b64 v[8:9], 2, v[8:9]
	s_waitcnt lgkmcnt(0)
	v_lshl_add_u64 v[10:11], s[12:13], 0, v[8:9]
	v_lshl_add_u64 v[8:9], s[14:15], 0, v[8:9]
	global_load_dword v56, v[8:9], off
	global_load_dword v53, v[10:11], off
	v_or_b32_e32 v8, s50, v1
	v_mov_b32_e32 v9, s51
	v_lshlrev_b64 v[8:9], 2, v[8:9]
	v_lshl_add_u64 v[10:11], s[12:13], 0, v[8:9]
	v_lshl_add_u64 v[8:9], s[14:15], 0, v[8:9]
	global_load_dword v59, v[8:9], off
	global_load_dword v58, v[10:11], off
	v_or_b32_e32 v8, s52, v1
	v_mov_b32_e32 v9, s53
	v_lshlrev_b64 v[8:9], 2, v[8:9]
	v_lshl_add_u64 v[10:11], s[12:13], 0, v[8:9]
	v_lshl_add_u64 v[8:9], s[14:15], 0, v[8:9]
	global_load_dword v61, v[8:9], off
	global_load_dword v60, v[10:11], off
	v_or_b32_e32 v8, s54, v1
	v_mov_b32_e32 v9, s55
	v_lshlrev_b64 v[8:9], 2, v[8:9]
	v_lshl_add_u64 v[10:11], s[12:13], 0, v[8:9]
	v_lshl_add_u64 v[8:9], s[14:15], 0, v[8:9]
	global_load_dword v63, v[8:9], off
	global_load_dword v62, v[10:11], off
	v_or_b32_e32 v8, s56, v1
	v_mov_b32_e32 v9, s57
	v_lshlrev_b64 v[8:9], 2, v[8:9]
	v_lshl_add_u64 v[10:11], s[12:13], 0, v[8:9]
	v_lshl_add_u64 v[8:9], s[14:15], 0, v[8:9]
	global_load_dword v65, v[8:9], off
	v_or_b32_e32 v8, s58, v1
	v_mov_b32_e32 v9, s59
	v_lshlrev_b64 v[8:9], 2, v[8:9]
	global_load_dword v64, v[10:11], off
	v_lshl_add_u64 v[10:11], s[12:13], 0, v[8:9]
	v_lshl_add_u64 v[8:9], s[14:15], 0, v[8:9]
	global_load_dword v67, v[8:9], off
	v_or_b32_e32 v8, s60, v1
	v_mov_b32_e32 v9, s61
	v_lshlrev_b64 v[8:9], 2, v[8:9]
	global_load_dword v66, v[10:11], off
	v_lshl_add_u64 v[10:11], s[12:13], 0, v[8:9]
	v_lshl_add_u64 v[8:9], s[14:15], 0, v[8:9]
	global_load_dword v69, v[8:9], off
	v_or_b32_e32 v8, s62, v1
	v_mov_b32_e32 v9, s63
	v_lshlrev_b64 v[8:9], 2, v[8:9]
	global_load_dword v68, v[10:11], off
	v_lshl_add_u64 v[10:11], s[12:13], 0, v[8:9]
	v_lshl_add_u64 v[8:9], s[14:15], 0, v[8:9]
	global_load_dword v52, v[8:9], off
	v_or_b32_e32 v8, s64, v1
	v_mov_b32_e32 v9, s65
	v_lshlrev_b64 v[8:9], 2, v[8:9]
	global_load_dword v51, v[10:11], off
	v_lshl_add_u64 v[10:11], s[12:13], 0, v[8:9]
	v_lshl_add_u64 v[8:9], s[14:15], 0, v[8:9]
	global_load_dword v50, v[8:9], off
	v_or_b32_e32 v8, s66, v1
	v_mov_b32_e32 v9, s67
	v_lshlrev_b64 v[8:9], 2, v[8:9]
	global_load_dword v49, v[10:11], off
	v_lshl_add_u64 v[10:11], s[12:13], 0, v[8:9]
	v_lshl_add_u64 v[8:9], s[14:15], 0, v[8:9]
	global_load_dword v48, v[8:9], off
	v_or_b32_e32 v8, s68, v1
	v_mov_b32_e32 v9, s69
	v_lshlrev_b64 v[8:9], 2, v[8:9]
	global_load_dword v45, v[10:11], off
	v_lshl_add_u64 v[10:11], s[12:13], 0, v[8:9]
	v_lshl_add_u64 v[8:9], s[14:15], 0, v[8:9]
	global_load_dword v44, v[8:9], off
	v_or_b32_e32 v8, s70, v1
	v_mov_b32_e32 v9, s71
	v_lshlrev_b64 v[8:9], 2, v[8:9]
	global_load_dword v43, v[10:11], off
	v_lshl_add_u64 v[10:11], s[12:13], 0, v[8:9]
	v_lshl_add_u64 v[8:9], s[14:15], 0, v[8:9]
	global_load_dword v42, v[8:9], off
	v_or_b32_e32 v8, s72, v1
	v_mov_b32_e32 v9, s73
	v_lshlrev_b64 v[8:9], 2, v[8:9]
	global_load_dword v17, v[10:11], off
	v_lshl_add_u64 v[10:11], s[12:13], 0, v[8:9]
	v_lshl_add_u64 v[8:9], s[14:15], 0, v[8:9]
	global_load_dword v16, v[8:9], off
	v_or_b32_e32 v8, s74, v1
	v_mov_b32_e32 v9, s75
	v_lshlrev_b64 v[8:9], 2, v[8:9]
	global_load_dword v15, v[10:11], off
	v_lshl_add_u64 v[10:11], s[12:13], 0, v[8:9]
	v_lshl_add_u64 v[8:9], s[14:15], 0, v[8:9]
	global_load_dword v14, v[8:9], off
	v_or_b32_e32 v8, s76, v1
	v_mov_b32_e32 v9, s77
	v_lshlrev_b64 v[8:9], 2, v[8:9]
	global_load_dword v13, v[10:11], off
	v_lshl_add_u64 v[10:11], s[12:13], 0, v[8:9]
	v_lshl_add_u64 v[8:9], s[14:15], 0, v[8:9]
	global_load_dword v12, v[8:9], off
	v_or_b32_e32 v8, s78, v1
	v_mov_b32_e32 v9, s79
	v_lshlrev_b64 v[8:9], 2, v[8:9]
	v_lshl_add_u64 v[54:55], s[12:13], 0, v[8:9]
	global_load_dword v11, v[10:11], off
	v_lshl_add_u64 v[8:9], s[14:15], 0, v[8:9]
	global_load_dword v1, v[54:55], off
	s_waitcnt vmcnt(30)
	v_mul_f32_e32 v54, v108, v56
	s_waitcnt vmcnt(29)
	v_fma_f32 v57, v110, v53, -v54
	ds_read2st64_b32 v[54:55], v75 offset1:1
	global_load_dword v10, v[8:9], off
	v_lshl_add_u64 v[8:9], v[104:105], 0, s[6:7]
	s_waitcnt lgkmcnt(0)
	v_add_f32_e32 v70, v57, v54
	v_mul_f32_e32 v54, v110, v56
	v_fmac_f32_e32 v54, v108, v53
	v_add_f32_e32 v53, v54, v55
	v_lshl_add_u64 v[54:55], v[8:9], 0, s[8:9]
	v_add_co_u32_e32 v56, vcc, s43, v54
	ds_write2st64_b32 v75, v70, v53 offset1:1
	s_nop 0
	v_addc_co_u32_e32 v57, vcc, 0, v55, vcc
	v_add_co_u32_e32 v54, vcc, s38, v54
	v_readlane_b32 s8, v230, 17
	s_nop 0
	v_addc_co_u32_e32 v55, vcc, 0, v55, vcc
	global_store_dword v[54:55], v53, off
	ds_read2_b32 v[54:55], v75 offset0:132 offset1:196
	s_waitcnt vmcnt(30)
	v_mul_f32_e32 v53, v108, v59
	s_waitcnt vmcnt(29)
	v_fma_f32 v53, v110, v58, -v53
	v_readlane_b32 s9, v230, 18
	global_store_dword v[56:57], v70, off
	s_waitcnt lgkmcnt(0)
	v_add_f32_e32 v53, v53, v54
	v_mul_f32_e32 v54, v110, v59
	v_fmac_f32_e32 v54, v108, v58
	v_add_f32_e32 v58, v54, v55
	v_lshl_add_u64 v[54:55], v[8:9], 0, s[8:9]
	v_add_co_u32_e32 v56, vcc, s43, v54
	ds_write2_b32 v75, v53, v58 offset0:132 offset1:196
	s_nop 0
	v_addc_co_u32_e32 v57, vcc, 0, v55, vcc
	v_add_co_u32_e32 v54, vcc, s38, v54
	global_store_dword v[56:57], v53, off
	s_nop 0
	v_addc_co_u32_e32 v55, vcc, 0, v55, vcc
	global_store_dword v[54:55], v58, off
	ds_read2st64_b32 v[54:55], v146 offset0:4 offset1:5
	s_waitcnt vmcnt(31)
	v_mul_f32_e32 v53, v108, v61
	s_waitcnt vmcnt(30)
	v_fma_f32 v53, v110, v60, -v53
	v_readlane_b32 s8, v230, 19
	v_readlane_b32 s9, v230, 20
	s_waitcnt lgkmcnt(0)
	v_add_f32_e32 v53, v53, v54
	v_mul_f32_e32 v54, v110, v61
	v_fmac_f32_e32 v54, v108, v60
	v_add_f32_e32 v58, v54, v55
	v_lshl_add_u64 v[54:55], v[8:9], 0, s[8:9]
	v_add_co_u32_e32 v56, vcc, s43, v54
	ds_write2st64_b32 v146, v53, v58 offset0:4 offset1:5
	s_nop 0
	v_addc_co_u32_e32 v57, vcc, 0, v55, vcc
	v_add_co_u32_e32 v54, vcc, s38, v54
	global_store_dword v[56:57], v53, off
	s_nop 0
	v_addc_co_u32_e32 v55, vcc, 0, v55, vcc
	global_store_dword v[54:55], v58, off
	ds_read2st64_b32 v[54:55], v142 offset0:6 offset1:7
	s_waitcnt vmcnt(31)
	v_mul_f32_e32 v53, v108, v63
	s_waitcnt vmcnt(30)
	v_fma_f32 v53, v110, v62, -v53
	v_readlane_b32 s8, v230, 21
	v_readlane_b32 s9, v230, 22
	s_waitcnt lgkmcnt(0)
	v_add_f32_e32 v53, v53, v54
	v_mul_f32_e32 v54, v110, v63
	v_fmac_f32_e32 v54, v108, v62
	v_add_f32_e32 v58, v54, v55
	v_lshl_add_u64 v[54:55], v[8:9], 0, s[8:9]
	v_add_co_u32_e32 v56, vcc, s43, v54
	ds_write2st64_b32 v142, v53, v58 offset0:6 offset1:7
	s_nop 0
	v_addc_co_u32_e32 v57, vcc, 0, v55, vcc
	v_add_co_u32_e32 v54, vcc, s38, v54
	global_store_dword v[56:57], v53, off
	s_nop 0
	v_addc_co_u32_e32 v55, vcc, 0, v55, vcc
	global_store_dword v[54:55], v58, off
	ds_read2st64_b32 v[54:55], v190 offset0:8 offset1:9
	s_waitcnt vmcnt(31)
	v_mul_f32_e32 v53, v108, v65
	s_waitcnt vmcnt(30)
	v_fma_f32 v53, v110, v64, -v53
	v_readlane_b32 s8, v230, 23
	v_readlane_b32 s9, v230, 24
	s_waitcnt lgkmcnt(0)
	v_add_f32_e32 v53, v53, v54
	v_mul_f32_e32 v54, v110, v65
	v_fmac_f32_e32 v54, v108, v64
	v_add_f32_e32 v58, v54, v55
	v_lshl_add_u64 v[54:55], v[8:9], 0, s[8:9]
	v_add_co_u32_e32 v56, vcc, s43, v54
	ds_write2st64_b32 v190, v53, v58 offset0:8 offset1:9
	s_nop 0
	v_addc_co_u32_e32 v57, vcc, 0, v55, vcc
	v_add_co_u32_e32 v54, vcc, s38, v54
	global_store_dword v[56:57], v53, off
	s_nop 0
	v_addc_co_u32_e32 v55, vcc, 0, v55, vcc
	global_store_dword v[54:55], v58, off
	ds_read2st64_b32 v[54:55], v144 offset0:10 offset1:11
	s_waitcnt vmcnt(31)
	v_mul_f32_e32 v53, v108, v67
	s_waitcnt vmcnt(30)
	v_fma_f32 v53, v110, v66, -v53
	v_readlane_b32 s8, v230, 25
	v_readlane_b32 s9, v230, 26
	s_waitcnt lgkmcnt(0)
	v_add_f32_e32 v53, v53, v54
	v_mul_f32_e32 v54, v110, v67
	v_fmac_f32_e32 v54, v108, v66
	v_add_f32_e32 v58, v54, v55
	v_lshl_add_u64 v[54:55], v[8:9], 0, s[8:9]
	v_add_co_u32_e32 v56, vcc, s43, v54
	ds_write2st64_b32 v144, v53, v58 offset0:10 offset1:11
	s_nop 0
	v_addc_co_u32_e32 v57, vcc, 0, v55, vcc
	v_add_co_u32_e32 v54, vcc, s38, v54
	global_store_dword v[56:57], v53, off
	s_nop 0
	v_addc_co_u32_e32 v55, vcc, 0, v55, vcc
	global_store_dword v[54:55], v58, off
	ds_read2st64_b32 v[54:55], v140 offset0:12 offset1:13
	s_waitcnt vmcnt(31)
	v_mul_f32_e32 v53, v108, v69
	s_waitcnt vmcnt(30)
	v_fma_f32 v53, v110, v68, -v53
	v_readlane_b32 s8, v230, 27
	v_readlane_b32 s9, v230, 28
	s_waitcnt lgkmcnt(0)
	v_add_f32_e32 v53, v53, v54
	v_mul_f32_e32 v54, v110, v69
	v_fmac_f32_e32 v54, v108, v68
	v_add_f32_e32 v58, v54, v55
	v_lshl_add_u64 v[54:55], v[8:9], 0, s[8:9]
	v_add_co_u32_e32 v56, vcc, s43, v54
	ds_write2st64_b32 v140, v53, v58 offset0:12 offset1:13
	s_nop 0
	v_addc_co_u32_e32 v57, vcc, 0, v55, vcc
	v_add_co_u32_e32 v54, vcc, s38, v54
	global_store_dword v[56:57], v53, off
	s_nop 0
	v_addc_co_u32_e32 v55, vcc, 0, v55, vcc
	global_store_dword v[54:55], v58, off
	ds_read2st64_b32 v[54:55], v136 offset0:14 offset1:15
	s_waitcnt vmcnt(31)
	v_mul_f32_e32 v53, v108, v52
	v_mul_f32_e32 v52, v110, v52
	v_readlane_b32 s8, v230, 29
	s_waitcnt vmcnt(30)
	v_fma_f32 v53, v110, v51, -v53
	v_fmac_f32_e32 v52, v108, v51
	v_readlane_b32 s9, v230, 30
	s_waitcnt lgkmcnt(0)
	v_add_f32_e32 v56, v53, v54
	v_add_f32_e32 v51, v52, v55
	v_lshl_add_u64 v[52:53], v[8:9], 0, s[8:9]
	v_add_co_u32_e32 v54, vcc, s43, v52
	ds_write2st64_b32 v136, v56, v51 offset0:14 offset1:15
	s_nop 0
	v_addc_co_u32_e32 v55, vcc, 0, v53, vcc
	v_add_co_u32_e32 v52, vcc, s38, v52
	v_readlane_b32 s8, v230, 31
	s_nop 0
	v_addc_co_u32_e32 v53, vcc, 0, v53, vcc
	global_store_dword v[52:53], v51, off
	ds_read2st64_b32 v[52:53], v138 offset0:16 offset1:17
	s_waitcnt vmcnt(30)
	v_mul_f32_e32 v51, v108, v50
	v_mul_f32_e32 v50, v110, v50
	s_waitcnt vmcnt(29)
	v_fma_f32 v51, v110, v49, -v51
	v_fmac_f32_e32 v50, v108, v49
	v_readlane_b32 s9, v230, 32
	global_store_dword v[54:55], v56, off
	s_waitcnt lgkmcnt(0)
	v_add_f32_e32 v54, v51, v52
	v_add_f32_e32 v49, v50, v53
	v_lshl_add_u64 v[50:51], v[8:9], 0, s[8:9]
	v_add_co_u32_e32 v52, vcc, s43, v50
	ds_write2st64_b32 v138, v54, v49 offset0:16 offset1:17
	s_nop 0
	v_addc_co_u32_e32 v53, vcc, 0, v51, vcc
	v_add_co_u32_e32 v50, vcc, s38, v50
	v_readlane_b32 s8, v230, 33
	s_nop 0
	v_addc_co_u32_e32 v51, vcc, 0, v51, vcc
	global_store_dword v[50:51], v49, off
	ds_read2st64_b32 v[50:51], v134 offset0:18 offset1:19
	s_waitcnt vmcnt(30)
	v_mul_f32_e32 v49, v108, v48
	v_mul_f32_e32 v48, v110, v48
	s_waitcnt vmcnt(29)
	v_fma_f32 v49, v110, v45, -v49
	v_fmac_f32_e32 v48, v108, v45
	v_readlane_b32 s9, v230, 34
	global_store_dword v[52:53], v54, off
	s_waitcnt lgkmcnt(0)
	v_add_f32_e32 v52, v49, v50
	v_add_f32_e32 v45, v48, v51
	v_lshl_add_u64 v[48:49], v[8:9], 0, s[8:9]
	v_add_co_u32_e32 v50, vcc, s43, v48
	ds_write2st64_b32 v134, v52, v45 offset0:18 offset1:19
	s_nop 0
	v_addc_co_u32_e32 v51, vcc, 0, v49, vcc
	v_add_co_u32_e32 v48, vcc, s38, v48
	v_readlane_b32 s8, v230, 35
	s_nop 0
	v_addc_co_u32_e32 v49, vcc, 0, v49, vcc
	global_store_dword v[48:49], v45, off
	ds_read2st64_b32 v[48:49], v132 offset0:20 offset1:21
	s_waitcnt vmcnt(30)
	v_mul_f32_e32 v45, v108, v44
	v_mul_f32_e32 v44, v110, v44
	s_waitcnt vmcnt(29)
	v_fma_f32 v45, v110, v43, -v45
	v_fmac_f32_e32 v44, v108, v43
	v_readlane_b32 s9, v230, 36
	global_store_dword v[50:51], v52, off
	s_waitcnt lgkmcnt(0)
	v_add_f32_e32 v50, v45, v48
	v_add_f32_e32 v43, v44, v49
	v_lshl_add_u64 v[44:45], v[8:9], 0, s[8:9]
	v_add_co_u32_e32 v48, vcc, s43, v44
	ds_write2st64_b32 v132, v50, v43 offset0:20 offset1:21
	s_nop 0
	v_addc_co_u32_e32 v49, vcc, 0, v45, vcc
	v_add_co_u32_e32 v44, vcc, s38, v44
	v_readlane_b32 s8, v230, 37
	s_nop 0
	v_addc_co_u32_e32 v45, vcc, 0, v45, vcc
	global_store_dword v[44:45], v43, off
	ds_read2st64_b32 v[44:45], v131 offset0:22 offset1:23
	s_waitcnt vmcnt(30)
	v_mul_f32_e32 v43, v108, v42
	v_mul_f32_e32 v42, v110, v42
	s_waitcnt vmcnt(29)
	v_fma_f32 v43, v110, v17, -v43
	v_fmac_f32_e32 v42, v108, v17
	v_readlane_b32 s9, v230, 38
	global_store_dword v[48:49], v50, off
	s_waitcnt lgkmcnt(0)
	v_add_f32_e32 v48, v43, v44
	v_add_f32_e32 v17, v42, v45
	v_lshl_add_u64 v[42:43], v[8:9], 0, s[8:9]
	v_add_co_u32_e32 v44, vcc, s43, v42
	ds_write2st64_b32 v131, v48, v17 offset0:22 offset1:23
	s_nop 0
	v_addc_co_u32_e32 v45, vcc, 0, v43, vcc
	v_add_co_u32_e32 v42, vcc, s38, v42
	v_readlane_b32 s8, v230, 39
	s_nop 0
	v_addc_co_u32_e32 v43, vcc, 0, v43, vcc
	global_store_dword v[42:43], v17, off
	ds_read2st64_b32 v[42:43], v130 offset0:24 offset1:25
	s_waitcnt vmcnt(30)
	v_mul_f32_e32 v17, v108, v16
	v_mul_f32_e32 v16, v110, v16
	s_waitcnt vmcnt(29)
	v_fma_f32 v17, v110, v15, -v17
	v_fmac_f32_e32 v16, v108, v15
	v_readlane_b32 s9, v230, 40
	global_store_dword v[44:45], v48, off
	s_waitcnt lgkmcnt(0)
	v_add_f32_e32 v44, v17, v42
	v_add_f32_e32 v15, v16, v43
	v_lshl_add_u64 v[16:17], v[8:9], 0, s[8:9]
	v_add_co_u32_e32 v42, vcc, s43, v16
	ds_write2st64_b32 v130, v44, v15 offset0:24 offset1:25
	s_nop 0
	v_addc_co_u32_e32 v43, vcc, 0, v17, vcc
	v_add_co_u32_e32 v16, vcc, s38, v16
	v_readlane_b32 s8, v230, 41
	s_nop 0
	v_addc_co_u32_e32 v17, vcc, 0, v17, vcc
	global_store_dword v[16:17], v15, off
	ds_read2st64_b32 v[16:17], v107 offset0:26 offset1:27
	s_waitcnt vmcnt(30)
	v_mul_f32_e32 v15, v108, v14
	v_mul_f32_e32 v14, v110, v14
	s_waitcnt vmcnt(29)
	v_fma_f32 v15, v110, v13, -v15
	v_fmac_f32_e32 v14, v108, v13
	v_readlane_b32 s9, v230, 42
	global_store_dword v[42:43], v44, off
	s_waitcnt lgkmcnt(0)
	v_add_f32_e32 v42, v15, v16
	v_add_f32_e32 v13, v14, v17
	v_lshl_add_u64 v[14:15], v[8:9], 0, s[8:9]
	v_add_co_u32_e32 v16, vcc, s43, v14
	ds_write2st64_b32 v107, v42, v13 offset0:26 offset1:27
	s_nop 0
	v_addc_co_u32_e32 v17, vcc, 0, v15, vcc
	v_add_co_u32_e32 v14, vcc, s38, v14
	v_readlane_b32 s8, v230, 43
	s_nop 0
	v_addc_co_u32_e32 v15, vcc, 0, v15, vcc
	global_store_dword v[14:15], v13, off
	ds_read2st64_b32 v[14:15], v73 offset0:28 offset1:29
	s_waitcnt vmcnt(30)
	v_mul_f32_e32 v13, v108, v12
	v_mul_f32_e32 v12, v110, v12
	s_waitcnt vmcnt(29)
	v_fma_f32 v13, v110, v11, -v13
	v_fmac_f32_e32 v12, v108, v11
	v_readlane_b32 s9, v230, 44
	global_store_dword v[16:17], v42, off
	s_waitcnt lgkmcnt(0)
	v_add_f32_e32 v16, v13, v14
	v_add_f32_e32 v11, v12, v15
	v_lshl_add_u64 v[12:13], v[8:9], 0, s[8:9]
	v_add_co_u32_e32 v14, vcc, s43, v12
	v_readlane_b32 s8, v230, 45
	s_nop 0
	v_addc_co_u32_e32 v15, vcc, 0, v13, vcc
	v_add_co_u32_e32 v12, vcc, s38, v12
	ds_write2st64_b32 v73, v16, v11 offset0:28 offset1:29
	s_nop 0
	v_addc_co_u32_e32 v13, vcc, 0, v13, vcc
	global_store_dword v[12:13], v11, off
	ds_read2st64_b32 v[12:13], v72 offset0:30 offset1:31
	s_waitcnt vmcnt(29)
	v_mul_f32_e32 v11, v108, v10
	v_mul_f32_e32 v10, v110, v10
	v_readlane_b32 s9, v230, 46
	v_fmac_f32_e32 v10, v108, v1
	v_fma_f32 v11, v110, v1, -v11
	v_lshl_add_u64 v[8:9], v[8:9], 0, s[8:9]
	s_waitcnt lgkmcnt(0)
	v_add_f32_e32 v1, v10, v13
	v_add_co_u32_e32 v10, vcc, s43, v8
	v_add_f32_e32 v12, v11, v12
	s_nop 0
	v_addc_co_u32_e32 v11, vcc, 0, v9, vcc
	v_add_co_u32_e32 v8, vcc, s38, v8
	global_store_dword v[14:15], v16, off
	s_nop 0
	v_addc_co_u32_e32 v9, vcc, 0, v9, vcc
	ds_write2st64_b32 v72, v12, v1 offset0:30 offset1:31
	global_store_dword v[10:11], v12, off
	global_store_dword v[8:9], v1, off
	s_waitcnt lgkmcnt(0)
	ds_read_b128 v[8:11], v154
	ds_read_b128 v[12:15], v154 offset:16
	ds_read_b128 v[42:45], v154 offset:128
	ds_read_b128 v[48:51], v154 offset:144
	ds_read_b128 v[52:55], v154 offset:256
	ds_read_b128 v[56:59], v154 offset:272
	ds_read_b128 v[60:63], v154 offset:384
	ds_read_b128 v[64:67], v154 offset:400
	s_waitcnt lgkmcnt(7)
	v_cvt_pk_bf16_f32 v8, v8, v9
	v_cvt_pk_bf16_f32 v9, v10, v11
	s_waitcnt lgkmcnt(6)
	v_cvt_pk_bf16_f32 v10, v12, v13
	v_cvt_pk_bf16_f32 v11, v14, v15
	s_waitcnt lgkmcnt(5)
	v_cvt_pk_bf16_f32 v12, v42, v43
	v_cvt_pk_bf16_f32 v13, v44, v45
	v_mfma_f32_16x16x32_bf16 v[8:11], v[38:41], v[8:11], 0
	s_waitcnt lgkmcnt(4)
	v_cvt_pk_bf16_f32 v14, v48, v49
	v_cvt_pk_bf16_f32 v15, v50, v51
	s_waitcnt lgkmcnt(0)
	s_nop 1
	v_mfma_f32_16x16x32_bf16 v[8:11], v[30:33], v[12:15], v[8:11]
	s_waitcnt lgkmcnt(3)
	v_cvt_pk_bf16_f32 v12, v52, v53
	v_cvt_pk_bf16_f32 v13, v54, v55
	s_waitcnt lgkmcnt(2)
	v_cvt_pk_bf16_f32 v14, v56, v57
	v_cvt_pk_bf16_f32 v15, v58, v59
	s_nop 1
	v_mfma_f32_16x16x32_bf16 v[8:11], v[26:29], v[12:15], v[8:11]
	s_waitcnt lgkmcnt(1)
	v_cvt_pk_bf16_f32 v12, v60, v61
	v_cvt_pk_bf16_f32 v13, v62, v63
	s_waitcnt lgkmcnt(0)
	v_cvt_pk_bf16_f32 v14, v64, v65
	v_cvt_pk_bf16_f32 v15, v66, v67
	s_nop 1
	v_mfma_f32_16x16x32_bf16 v[8:11], v[34:37], v[12:15], v[8:11]
	s_nop 7
	v_pk_fma_f32 v[6:7], v[24:25], v[6:7], v[10:11]
	v_pk_fma_f32 v[4:5], v[22:23], v[4:5], v[8:9]
	v_pk_mul_f32 v[10:11], v[6:7], v[6:7]
	v_pk_mul_f32 v[8:9], v[4:5], v[4:5]
	v_fmamk_f32 v1, v10, 0xbdd2d3e8, v151
	v_mul_f32_e32 v1, v6, v1
	v_exp_f32_e32 v1, v1
	s_nop 0
	v_add_f32_e32 v1, 1.0, v1
	v_rcp_f32_e32 v10, v1
	v_fmamk_f32 v1, v11, 0xbdd2d3e8, v151
	v_mul_f32_e32 v1, v7, v1
	v_exp_f32_e32 v1, v1
	s_nop 0
	v_add_f32_e32 v1, 1.0, v1
	v_rcp_f32_e32 v11, v1
	v_fmamk_f32 v1, v8, 0xbdd2d3e8, v151
	v_mul_f32_e32 v1, v4, v1
	v_exp_f32_e32 v1, v1
	v_pk_mul_f32 v[10:11], v[6:7], v[10:11]
	v_add_f32_e32 v1, 1.0, v1
	v_rcp_f32_e32 v8, v1
	v_fmamk_f32 v1, v9, 0xbdd2d3e8, v151
	v_mul_f32_e32 v1, v5, v1
	v_exp_f32_e32 v1, v1
	v_cvt_pk_bf16_f32 v7, v10, v11
	v_add_f32_e32 v1, 1.0, v1
	v_rcp_f32_e32 v9, v1
	s_nop 0
	v_pk_mul_f32 v[8:9], v[4:5], v[8:9]
	s_nop 0
	v_cvt_pk_bf16_f32 v6, v8, v9
	s_nop 1
	v_mfma_f32_16x16x16_bf16 v[4:7], v[46:47], v[6:7], 0
	s_nop 7
	v_add_f32_e32 v1, v18, v4
	v_mul_f32_e32 v1, 0xbfb8aa3b, v1
	v_exp_f32_e32 v1, v1
	s_nop 0
	v_add_f32_e32 v1, 1.0, v1
	v_rcp_f32_e32 v4, v1
	v_add_f32_e32 v1, v19, v5
	v_mul_f32_e32 v1, 0xbfb8aa3b, v1
	v_exp_f32_e32 v1, v1
	s_nop 0
	v_add_f32_e32 v1, 1.0, v1
	v_rcp_f32_e32 v5, v1
	v_add_f32_e32 v1, v20, v6
	v_mul_f32_e32 v1, 0xbfb8aa3b, v1
	v_exp_f32_e32 v1, v1
	v_pk_mul_f32 v[4:5], v[4:5], v[8:9]
	v_add_f32_e32 v1, 1.0, v1
	v_rcp_f32_e32 v6, v1
	v_add_f32_e32 v1, v21, v7
	v_mul_f32_e32 v1, 0xbfb8aa3b, v1
	v_exp_f32_e32 v1, v1
	v_cvt_pk_bf16_f32 v4, v4, v5
	v_add_f32_e32 v1, 1.0, v1
	v_rcp_f32_e32 v7, v1
	s_nop 0
	v_pk_mul_f32 v[6:7], v[6:7], v[10:11]
	s_nop 0
	v_cvt_pk_bf16_f32 v5, v6, v7
	global_store_dwordx2 v[2:3], v[4:5], off
	s_branch .LBB0_654

.LBB0_1066:
	s_load_dwordx2 s[8:9], s[0:1], 0xe8
	s_add_u32 s4, s26, 0xf000000
	s_addc_u32 s5, s27, 0
	s_cmpk_gt_i32 s12, 0x1fff
	s_cbranch_scc1 .LBB0_1073
	s_ashr_i32 s13, s12, 31
	s_lshl_b64 s[6:7], s[12:13], 12
	s_add_u32 s6, s26, s6
	v_mov_b32_e32 v33, 0
	s_addc_u32 s7, s27, s7
	v_lshlrev_b32_e32 v32, 3, v162
	s_waitcnt vmcnt(13)
	v_lshl_add_u64 v[2:3], s[6:7], 0, v[32:33]
	s_mov_b64 s[6:7], 0x16c00000
	s_waitcnt vmcnt(11)
	v_lshl_add_u64 v[4:5], v[2:3], 0, s[6:7]
	global_load_dwordx2 v[6:7], v[4:5], off offset:512
	global_load_dwordx2 v[8:9], v[4:5], off offset:1024
	global_load_dwordx2 v[10:11], v[4:5], off offset:1536
	global_load_dwordx2 v[12:13], v[4:5], off offset:2048
	global_load_dwordx2 v[14:15], v[4:5], off offset:2560
	v_add_co_u32_e32 v2, vcc, 0x16c00000, v2
	global_load_dwordx2 v[16:17], v[4:5], off offset:3072
	s_nop 0
	v_addc_co_u32_e32 v3, vcc, 0, v3, vcc
	global_load_dwordx2 v[18:19], v[2:3], off
	global_load_dwordx2 v[20:21], v[4:5], off offset:3584
	v_mbcnt_lo_u32_b32 v1, -1, 0
	v_mbcnt_hi_u32_b32 v2, -1, v1
	v_and_b32_e32 v1, 64, v2
	v_xor_b32_e32 v3, 1, v2
	v_add_u32_e32 v26, 64, v1
	v_xor_b32_e32 v4, 2, v2
	v_cmp_lt_i32_e32 vcc, v3, v26
	v_xor_b32_e32 v5, 4, v2
	v_xor_b32_e32 v23, 8, v2
	v_cndmask_b32_e32 v1, v2, v3, vcc
	v_cmp_lt_i32_e32 vcc, v4, v26
	v_xor_b32_e32 v24, 16, v2
	v_xor_b32_e32 v25, 32, v2
	v_cndmask_b32_e32 v3, v2, v4, vcc
	v_cmp_lt_i32_e32 vcc, v5, v26
	v_lshlrev_b32_e32 v22, 2, v162
	v_lshlrev_b32_e32 v80, 2, v3
	v_cndmask_b32_e32 v4, v2, v5, vcc
	v_cmp_lt_i32_e32 vcc, v23, v26
	v_mov_b32_e32 v3, v33
	s_lshl_b32 s13, s2, 10
	v_cndmask_b32_e32 v5, v2, v23, vcc
	v_cmp_lt_i32_e32 vcc, v24, v26
	s_lshl_b32 s14, s3, 2
	s_and_b32 s13, s13, 0x1800
	v_cndmask_b32_e32 v23, v2, v24, vcc
	v_cmp_lt_i32_e32 vcc, v25, v26
	s_add_u32 s28, s26, 0xde0c000
	s_addc_u32 s29, s27, 0
	v_cndmask_b32_e32 v2, v2, v25, vcc
	v_lshlrev_b32_e32 v84, 2, v2
	v_lshlrev_b32_e32 v2, 4, v162
	s_waitcnt lgkmcnt(0)
	v_lshl_add_u64 v[34:35], s[8:9], 0, v[2:3]
	s_mov_b32 s21, 0
	v_lshlrev_b32_e32 v1, 2, v1
	v_lshlrev_b32_e32 v81, 2, v4
	v_lshlrev_b32_e32 v82, 2, v5
	v_lshlrev_b32_e32 v83, 2, v23
	v_lshl_add_u64 v[46:47], s[4:5], 0, v[32:33]
	v_mov_b32_e32 v4, v33
	v_mov_b32_e32 v5, v33
	v_mov_b32_e32 v85, 0x358637bd
	s_mov_b32 s33, 0xf800000
	v_mov_b32_e32 v86, 0x260
	v_lshlrev_b32_e32 v87, 2, v22
	v_mov_b32_e32 v24, v33
	v_mov_b32_e32 v23, v33
	v_mov_b32_e32 v26, v33
	v_mov_b32_e32 v25, v33
	v_mov_b32_e32 v28, v33
	v_mov_b32_e32 v27, v33
	v_mov_b32_e32 v30, v33
	v_mov_b32_e32 v29, v33
	v_mov_b32_e32 v31, v33
	s_waitcnt vmcnt(7)
	v_lshlrev_b32_e32 v72, 16, v6
	s_waitcnt vmcnt(6)
	v_lshlrev_b32_e32 v68, 16, v8
	v_and_b32_e32 v69, 0xffff0000, v8
	s_waitcnt vmcnt(5)
	v_lshlrev_b32_e32 v64, 16, v10
	s_waitcnt vmcnt(3)
	v_lshlrev_b32_e32 v56, 16, v14
	v_and_b32_e32 v57, 0xffff0000, v14
	v_or_b32_e32 v14, 0x400, v22
	s_waitcnt vmcnt(2)
	v_lshlrev_b32_e32 v52, 16, v16
	v_and_b32_e32 v53, 0xffff0000, v16
	v_lshlrev_b32_e32 v2, 2, v14
	v_or_b32_e32 v16, 0x500, v22
	s_waitcnt vmcnt(1)
	v_lshlrev_b32_e32 v76, 16, v18
	v_and_b32_e32 v77, 0xffff0000, v18
	v_lshl_add_u64 v[36:37], s[8:9], 0, v[2:3]
	v_lshlrev_b32_e32 v2, 2, v16
	v_or_b32_e32 v18, 0x600, v22
	s_waitcnt vmcnt(0)
	v_lshlrev_b32_e32 v48, 16, v20
	v_and_b32_e32 v49, 0xffff0000, v20
	v_lshl_add_u64 v[38:39], s[8:9], 0, v[2:3]
	v_lshlrev_b32_e32 v2, 2, v18
	v_or_b32_e32 v20, 0x700, v22
	v_lshl_add_u64 v[40:41], s[8:9], 0, v[2:3]
	v_lshlrev_b32_e32 v2, 2, v20
	v_lshl_add_u64 v[42:43], s[8:9], 0, v[2:3]
	v_lshl_add_u64 v[2:3], s[26:27], 0, v[32:33]
	v_lshl_add_u64 v[44:45], v[2:3], 0, s[6:7]
	s_and_b32 s6, s2, 1
	s_lshl_b32 s6, s6, 10
	s_lshl_b32 s7, s2, 2
	s_or_b32 s6, s13, s6
	s_andn2_b32 s7, s7, 31
	s_add_i32 s6, s6, s7
	s_or_b32 s6, s6, s14
	s_or_b32 s30, s6, 1
	s_or_b32 s6, s3, 8
	v_and_b32_e32 v65, 0xffff0000, v10
	v_lshlrev_b32_e32 v60, 16, v12
	v_and_b32_e32 v61, 0xffff0000, v12
	v_or_b32_e32 v8, 0x100, v22
	v_or_b32_e32 v10, 0x200, v22
	v_or_b32_e32 v12, 0x300, v22
	s_mul_i32 s6, s20, s6
	v_and_b32_e32 v73, 0xffff0000, v6
	v_lshlrev_b32_e32 v74, 16, v7
	v_and_b32_e32 v75, 0xffff0000, v7
	v_lshlrev_b32_e32 v70, 16, v9
	v_and_b32_e32 v71, 0xffff0000, v9
	v_lshlrev_b32_e32 v66, 16, v11
	v_and_b32_e32 v67, 0xffff0000, v11
	v_lshlrev_b32_e32 v62, 16, v13
	v_and_b32_e32 v63, 0xffff0000, v13
	v_lshlrev_b32_e32 v58, 16, v15
	v_and_b32_e32 v59, 0xffff0000, v15
	v_lshlrev_b32_e32 v54, 16, v17
	v_and_b32_e32 v55, 0xffff0000, v17
	v_lshlrev_b32_e32 v78, 16, v19
	v_and_b32_e32 v79, 0xffff0000, v19
	v_lshlrev_b32_e32 v50, 16, v21
	v_and_b32_e32 v51, 0xffff0000, v21
	s_add_i32 s31, s2, s6
	v_mov_b32_e32 v2, v33
	v_mov_b32_e32 v3, v33
	v_mov_b32_e32 v6, v33
	v_lshlrev_b32_e32 v88, 2, v8
	v_lshlrev_b32_e32 v89, 2, v10
	v_lshlrev_b32_e32 v90, 2, v12
	v_lshlrev_b32_e32 v91, 2, v14
	v_lshlrev_b32_e32 v92, 2, v16
	v_lshlrev_b32_e32 v93, 2, v18
	v_lshlrev_b32_e32 v94, 2, v20
	v_mov_b32_e32 v8, v33
	v_mov_b32_e32 v7, v33
	v_mov_b32_e32 v10, v33
	v_mov_b32_e32 v9, v33
	v_mov_b32_e32 v12, v33
	v_mov_b32_e32 v11, v33
	v_mov_b32_e32 v14, v33
	v_mov_b32_e32 v13, v33
	v_mov_b32_e32 v16, v33
	v_mov_b32_e32 v15, v33
	v_mov_b32_e32 v18, v33
	v_mov_b32_e32 v17, v33
	v_mov_b32_e32 v20, v33
	v_mov_b32_e32 v19, v33
	v_mov_b32_e32 v22, v33
	v_mov_b32_e32 v21, v33
	v_mov_b32_e32 v32, v33
	s_mov_b32 s98, -1
	s_branch .LBB0_1069

.Lnorm_skip_1068:
	s_and_b64 s[6:7], s[16:17], exec
	s_cselect_b32 s14, s12, s14
	s_ashr_i32 s15, s14, 31
	s_lshl_b64 s[6:7], s[14:15], 12
	v_lshl_add_u64 v[2:3], v[44:45], 0, s[6:7]
	global_load_dwordx2 v[4:5], v[2:3], off
	global_load_dwordx2 v[8:9], v[2:3], off offset:512
	global_load_dwordx2 v[12:13], v[2:3], off offset:1024
	global_load_dwordx2 v[16:17], v[2:3], off offset:1536
	global_load_dwordx2 v[20:21], v[2:3], off offset:2048
	global_load_dwordx2 v[24:25], v[2:3], off offset:2560
	global_load_dwordx2 v[28:29], v[2:3], off offset:3072
	global_load_dwordx2 v[148:149], v[2:3], off offset:3584
	v_mov_b32_e32 v98, v73
	v_mov_b32_e32 v99, v77
	v_mov_b32_e32 v96, v72
	v_mov_b32_e32 v97, v76
	v_pk_mul_f32 v[98:99], v[98:99], v[98:99]
	v_mov_b32_e32 v100, v75
	v_mov_b32_e32 v101, v79
	v_pk_fma_f32 v[96:97], v[96:97], v[96:97], v[98:99]
	v_mov_b32_e32 v98, v74
	v_mov_b32_e32 v99, v78
	v_pk_mul_f32 v[100:101], v[100:101], v[100:101]
	s_nop 0
	v_pk_fma_f32 v[98:99], v[98:99], v[98:99], v[100:101]
	v_pk_mul_f32 v[100:101], v[68:69], v[68:69]
	v_pk_add_f32 v[96:97], v[96:97], v[98:99]
	v_pk_mul_f32 v[98:99], v[70:71], v[70:71]
	v_pk_add_f32 v[96:97], v[96:97], v[96:97] op_sel_hi:[0,1]
	v_pk_mov_b32 v[102:103], v[100:101], v[98:99] op_sel:[1,0]
	v_mov_b32_e32 v101, v99
	v_pk_add_f32 v[98:99], v[102:103], v[100:101]
	v_mul_f32_e32 v100, v64, v64
	v_pk_fma_f32 v[100:101], v[64:65], v[64:65], v[100:101] op_sel_hi:[1,1,0]
	v_pk_add_f32 v[98:99], v[98:99], v[98:99] op_sel_hi:[0,1]
	v_mul_f32_e32 v100, v66, v66
	v_pk_fma_f32 v[102:103], v[66:67], v[66:67], v[100:101] op_sel_hi:[1,1,0]
	v_mul_f32_e32 v100, v60, v60
	v_mul_f32_e32 v102, v61, v61
	v_mul_f32_e32 v98, v62, v62
	v_mul_f32_e32 v96, v63, v63
	v_pk_add_f32 v[100:101], v[100:101], v[102:103]
	v_pk_add_f32 v[96:97], v[98:99], v[96:97]
	v_pk_mul_f32 v[98:99], v[58:59], v[58:59]
	v_pk_add_f32 v[96:97], v[100:101], v[96:97]
	v_pk_mul_f32 v[100:101], v[56:57], v[56:57]
	v_pk_add_f32 v[96:97], v[96:97], v[96:97] op_sel_hi:[0,1]
	v_pk_mov_b32 v[102:103], v[100:101], v[98:99] op_sel:[1,0]
	v_mov_b32_e32 v101, v99
	v_pk_add_f32 v[98:99], v[102:103], v[100:101]
	v_mul_f32_e32 v100, v52, v52
	v_pk_fma_f32 v[100:101], v[52:53], v[52:53], v[100:101] op_sel_hi:[1,1,0]
	v_pk_add_f32 v[98:99], v[98:99], v[98:99] op_sel_hi:[0,1]
	v_mul_f32_e32 v100, v54, v54
	v_pk_fma_f32 v[102:103], v[54:55], v[54:55], v[100:101] op_sel_hi:[1,1,0]
	v_mul_f32_e32 v100, v48, v48
	v_mul_f32_e32 v102, v49, v49
	v_mul_f32_e32 v98, v50, v50
	v_mul_f32_e32 v96, v51, v51
	v_pk_add_f32 v[100:101], v[100:101], v[102:103]
	v_pk_add_f32 v[96:97], v[98:99], v[96:97]
	s_nop 0
	v_pk_add_f32 v[96:97], v[100:101], v[96:97]
	s_nop 0
	v_add_f32_e32 v95, v96, v97
	ds_bpermute_b32 v96, v1, v95
	s_waitcnt lgkmcnt(0)
	v_add_f32_e32 v95, v95, v96
	ds_bpermute_b32 v96, v80, v95
	s_waitcnt lgkmcnt(0)
	v_add_f32_e32 v95, v95, v96
	ds_bpermute_b32 v96, v81, v95
	s_waitcnt lgkmcnt(0)
	v_add_f32_e32 v95, v95, v96
	ds_bpermute_b32 v96, v82, v95
	s_waitcnt lgkmcnt(0)
	v_add_f32_e32 v95, v95, v96
	ds_bpermute_b32 v96, v83, v95
	s_waitcnt lgkmcnt(0)
	v_add_f32_e32 v95, v95, v96
	ds_bpermute_b32 v96, v84, v95
	s_waitcnt lgkmcnt(0)
	v_add_f32_e32 v95, v95, v96
	v_fmamk_f32 v95, v95, 0x3a000000, v85
	v_mul_f32_e32 v96, 0x4f800000, v95
	v_cmp_gt_f32_e32 vcc, s33, v95
	s_nop 1
	v_cndmask_b32_e32 v95, v95, v96, vcc
	v_sqrt_f32_e32 v96, v95
	s_nop 0
	v_add_u32_e32 v97, -1, v96
	v_fma_f32 v98, -v97, v96, v95
	v_cmp_ge_f32_e64 s[6:7], 0, v98
	v_add_u32_e32 v98, 1, v96
	s_nop 0
	v_cndmask_b32_e64 v97, v96, v97, s[6:7]
	v_fma_f32 v96, -v98, v96, v95
	v_cmp_lt_f32_e64 s[6:7], 0, v96
	s_nop 1
	v_cndmask_b32_e64 v96, v97, v98, s[6:7]
	v_mul_f32_e32 v97, 0x37800000, v96
	v_cndmask_b32_e32 v96, v96, v97, vcc
	v_cmp_class_f32_e32 vcc, v95, v86
	s_nop 1
	v_cndmask_b32_e32 v95, v96, v95, vcc
	v_div_scale_f32 v96, s[6:7], v95, v95, 1.0
	v_rcp_f32_e32 v97, v96
	s_ashr_i32 s6, s12, 11
	s_mul_hi_i32 s7, s6, 0x12000
	s_mul_i32 s6, s6, 0x12000
	v_fma_f32 v98, -v96, v97, 1.0
	v_fmac_f32_e32 v97, v98, v97
	v_div_scale_f32 v98, vcc, 1.0, v95, 1.0
	v_mul_f32_e32 v99, v98, v97
	v_fma_f32 v100, -v96, v99, v98
	v_fmac_f32_e32 v99, v100, v97
	v_fma_f32 v96, -v96, v99, v98
	v_div_fmas_f32 v96, v96, v97, v99
	v_div_fixup_f32 v100, v96, v95, 1.0
	v_pk_mul_f32 v[96:97], v[78:79], v[100:101] op_sel_hi:[1,0]
	v_pk_mul_f32 v[98:99], v[76:77], v[100:101] op_sel_hi:[1,0]
	s_waitcnt vmcnt(8)
	v_mov_b64_e32 v[76:77], v[116:117]
	v_mov_b64_e32 v[78:79], v[118:119]
	s_add_u32 s6, s28, s6
	s_addc_u32 s7, s29, s7
	s_add_u32 s18, s6, 0x2000
	s_addc_u32 s19, s7, 0
	s_ashr_i32 s13, s12, 31
	s_lshl_b64 s[12:13], s[12:13], 12
	s_add_i32 s31, s31, s22
	s_add_i32 s21, s21, 1
	s_and_b64 vcc, exec, s[16:17]
	s_waitcnt vmcnt(8)
	v_pk_mul_f32 v[102:103], v[76:77], v[98:99]
	v_pk_mul_f32 v[104:105], v[78:79], v[96:97]
	v_mov_b64_e32 v[76:77], v[120:121]
	v_mov_b64_e32 v[78:79], v[122:123]
	v_mov_b64_e32 v[96:97], v[124:125]
	v_mov_b64_e32 v[98:99], v[126:127]
	v_pk_add_f32 v[78:79], v[78:79], 1.0 op_sel_hi:[1,0]
	v_pk_add_f32 v[76:77], v[76:77], 1.0 op_sel_hi:[1,0]
	v_pk_fma_f32 v[78:79], v[78:79], v[104:105], v[98:99]
	v_pk_fma_f32 v[76:77], v[76:77], v[102:103], v[96:97]
	v_lshl_add_u64 v[96:97], v[46:47], 0, s[12:13]
	v_cvt_pk_bf16_f32 v76, v76, v77
	v_cvt_pk_bf16_f32 v77, v78, v79
	global_store_dwordx2 v[96:97], v[76:77], off
	v_pk_mul_f32 v[76:77], v[74:75], v[100:101] op_sel_hi:[1,0]
	v_pk_mul_f32 v[78:79], v[72:73], v[100:101] op_sel_hi:[1,0]
	v_mov_b64_e32 v[72:73], v[128:129]
	v_mov_b64_e32 v[74:75], v[130:131]
	s_mov_b32 s12, s14
	v_pk_mul_f32 v[98:99], v[72:73], v[78:79]
	v_pk_mul_f32 v[102:103], v[74:75], v[76:77]
	v_mov_b64_e32 v[72:73], v[132:133]
	v_mov_b64_e32 v[74:75], v[134:135]
	v_mov_b64_e32 v[76:77], v[136:137]
	v_mov_b64_e32 v[78:79], v[138:139]
	v_pk_add_f32 v[74:75], v[74:75], 1.0 op_sel_hi:[1,0]
	v_pk_add_f32 v[72:73], v[72:73], 1.0 op_sel_hi:[1,0]
	v_pk_fma_f32 v[74:75], v[74:75], v[102:103], v[78:79]
	v_pk_fma_f32 v[72:73], v[72:73], v[98:99], v[76:77]
	s_nop 0
	v_cvt_pk_bf16_f32 v72, v72, v73
	v_cvt_pk_bf16_f32 v73, v74, v75
	global_store_dwordx2 v[96:97], v[72:73], off offset:512
	v_pk_mul_f32 v[72:73], v[70:71], v[100:101] op_sel_hi:[1,0]
	v_pk_mul_f32 v[74:75], v[68:69], v[100:101] op_sel_hi:[1,0]
	v_mov_b64_e32 v[68:69], v[140:141]
	v_mov_b64_e32 v[70:71], v[142:143]
	v_pk_mul_f32 v[76:77], v[68:69], v[74:75]
	v_pk_mul_f32 v[78:79], v[70:71], v[72:73]
	v_mov_b64_e32 v[68:69], v[144:145]
	v_mov_b64_e32 v[70:71], v[146:147]
	v_mov_b64_e32 v[72:73], v[164:165]
	v_mov_b64_e32 v[74:75], v[166:167]
	v_pk_add_f32 v[70:71], v[70:71], 1.0 op_sel_hi:[1,0]
	v_pk_add_f32 v[68:69], v[68:69], 1.0 op_sel_hi:[1,0]
	v_pk_fma_f32 v[70:71], v[78:79], v[70:71], v[74:75]
	v_pk_fma_f32 v[68:69], v[76:77], v[68:69], v[72:73]
	v_cvt_pk_bf16_f32 v68, v68, v69
	v_cvt_pk_bf16_f32 v69, v70, v71
	global_store_dwordx2 v[96:97], v[68:69], off offset:1024
	v_pk_mul_f32 v[68:69], v[66:67], v[100:101] op_sel_hi:[1,0]
	v_pk_mul_f32 v[70:71], v[64:65], v[100:101] op_sel_hi:[1,0]
	v_mov_b64_e32 v[64:65], v[168:169]
	v_mov_b64_e32 v[66:67], v[170:171]
	v_pk_mul_f32 v[72:73], v[70:71], v[64:65]
	v_pk_mul_f32 v[74:75], v[68:69], v[66:67]
	v_mov_b64_e32 v[64:65], v[172:173]
	v_mov_b64_e32 v[66:67], v[174:175]
	v_mov_b64_e32 v[68:69], v[176:177]
	v_mov_b64_e32 v[70:71], v[178:179]
	v_pk_add_f32 v[66:67], v[66:67], 1.0 op_sel_hi:[1,0]
	v_pk_add_f32 v[64:65], v[64:65], 1.0 op_sel_hi:[1,0]
	v_pk_fma_f32 v[66:67], v[74:75], v[66:67], v[70:71]
	v_pk_fma_f32 v[64:65], v[72:73], v[64:65], v[68:69]
	v_cvt_pk_bf16_f32 v64, v64, v65
	v_cvt_pk_bf16_f32 v65, v66, v67
	global_store_dwordx2 v[96:97], v[64:65], off offset:1536
	v_pk_mul_f32 v[64:65], v[62:63], v[100:101] op_sel_hi:[1,0]
	v_pk_mul_f32 v[66:67], v[60:61], v[100:101] op_sel_hi:[1,0]
	v_mov_b64_e32 v[60:61], v[180:181]
	v_mov_b64_e32 v[62:63], v[182:183]
	v_pk_mul_f32 v[68:69], v[66:67], v[60:61]
	v_pk_mul_f32 v[70:71], v[64:65], v[62:63]
	v_mov_b64_e32 v[60:61], v[184:185]
	v_mov_b64_e32 v[62:63], v[186:187]
	v_mov_b64_e32 v[64:65], v[188:189]
	v_mov_b64_e32 v[66:67], v[190:191]
	v_pk_add_f32 v[62:63], v[62:63], 1.0 op_sel_hi:[1,0]
	v_pk_add_f32 v[60:61], v[60:61], 1.0 op_sel_hi:[1,0]
	v_pk_fma_f32 v[62:63], v[70:71], v[62:63], v[66:67]
	v_pk_fma_f32 v[60:61], v[68:69], v[60:61], v[64:65]
	v_cvt_pk_bf16_f32 v60, v60, v61
	v_cvt_pk_bf16_f32 v61, v62, v63
	global_store_dwordx2 v[96:97], v[60:61], off offset:2048
	v_pk_mul_f32 v[60:61], v[58:59], v[100:101] op_sel_hi:[1,0]
	v_pk_mul_f32 v[62:63], v[56:57], v[100:101] op_sel_hi:[1,0]
	v_mov_b64_e32 v[56:57], v[192:193]
	v_mov_b64_e32 v[58:59], v[194:195]
	v_pk_mul_f32 v[64:65], v[62:63], v[56:57]
	v_pk_mul_f32 v[66:67], v[60:61], v[58:59]
	v_mov_b64_e32 v[56:57], v[196:197]
	v_mov_b64_e32 v[58:59], v[198:199]
	v_mov_b64_e32 v[60:61], v[200:201]
	v_mov_b64_e32 v[62:63], v[202:203]
	v_pk_add_f32 v[58:59], v[58:59], 1.0 op_sel_hi:[1,0]
	v_pk_add_f32 v[56:57], v[56:57], 1.0 op_sel_hi:[1,0]
	v_pk_fma_f32 v[58:59], v[66:67], v[58:59], v[62:63]
	v_pk_fma_f32 v[56:57], v[64:65], v[56:57], v[60:61]
	v_cvt_pk_bf16_f32 v56, v56, v57
	v_cvt_pk_bf16_f32 v57, v58, v59
	global_store_dwordx2 v[96:97], v[56:57], off offset:2560
	v_pk_mul_f32 v[56:57], v[54:55], v[100:101] op_sel_hi:[1,0]
	v_pk_mul_f32 v[58:59], v[52:53], v[100:101] op_sel_hi:[1,0]
	v_mov_b64_e32 v[52:53], v[204:205]
	v_mov_b64_e32 v[54:55], v[206:207]
	v_pk_mul_f32 v[60:61], v[58:59], v[52:53]
	v_pk_mul_f32 v[62:63], v[56:57], v[54:55]
	v_mov_b64_e32 v[52:53], v[208:209]
	v_mov_b64_e32 v[54:55], v[210:211]
	v_mov_b64_e32 v[56:57], v[212:213]
	v_mov_b64_e32 v[58:59], v[214:215]
	v_pk_add_f32 v[54:55], v[54:55], 1.0 op_sel_hi:[1,0]
	v_pk_add_f32 v[52:53], v[52:53], 1.0 op_sel_hi:[1,0]
	v_pk_fma_f32 v[54:55], v[62:63], v[54:55], v[58:59]
	v_pk_fma_f32 v[52:53], v[60:61], v[52:53], v[56:57]
	v_pk_mul_f32 v[58:59], v[48:49], v[100:101] op_sel_hi:[1,0]
	v_cvt_pk_bf16_f32 v48, v52, v53
	v_cvt_pk_bf16_f32 v49, v54, v55
	global_store_dwordx2 v[96:97], v[48:49], off offset:3072
	v_pk_mul_f32 v[56:57], v[50:51], v[100:101] op_sel_hi:[1,0]
	v_mov_b64_e32 v[48:49], v[216:217]
	v_mov_b64_e32 v[50:51], v[218:219]
	v_pk_mul_f32 v[58:59], v[58:59], v[48:49]
	v_pk_mul_f32 v[56:57], v[56:57], v[50:51]
	v_mov_b64_e32 v[48:49], v[220:221]
	v_mov_b64_e32 v[50:51], v[222:223]
	v_mov_b64_e32 v[52:53], v[224:225]
	v_mov_b64_e32 v[54:55], v[226:227]
	v_pk_add_f32 v[50:51], v[50:51], 1.0 op_sel_hi:[1,0]
	v_pk_add_f32 v[48:49], v[48:49], 1.0 op_sel_hi:[1,0]
	v_pk_fma_f32 v[50:51], v[56:57], v[50:51], v[54:55]
	v_pk_fma_f32 v[48:49], v[58:59], v[48:49], v[52:53]
	v_cvt_pk_bf16_f32 v48, v48, v49
	v_cvt_pk_bf16_f32 v49, v50, v51
	global_store_dwordx2 v[96:97], v[48:49], off offset:3584
	s_waitcnt vmcnt(8)
	v_lshlrev_b32_e32 v76, 16, v4
	v_and_b32_e32 v77, 0xffff0000, v4
	v_lshlrev_b32_e32 v78, 16, v5
	v_and_b32_e32 v79, 0xffff0000, v5
	v_lshlrev_b32_e32 v72, 16, v8
	v_and_b32_e32 v73, 0xffff0000, v8
	v_lshlrev_b32_e32 v74, 16, v9
	v_and_b32_e32 v75, 0xffff0000, v9
	v_lshlrev_b32_e32 v68, 16, v12
	v_and_b32_e32 v69, 0xffff0000, v12
	v_lshlrev_b32_e32 v70, 16, v13
	v_and_b32_e32 v71, 0xffff0000, v13
	v_lshlrev_b32_e32 v64, 16, v16
	v_and_b32_e32 v65, 0xffff0000, v16
	v_lshlrev_b32_e32 v66, 16, v17
	v_and_b32_e32 v67, 0xffff0000, v17
	v_lshlrev_b32_e32 v60, 16, v20
	v_and_b32_e32 v61, 0xffff0000, v20
	v_lshlrev_b32_e32 v62, 16, v21
	v_and_b32_e32 v63, 0xffff0000, v21
	v_lshlrev_b32_e32 v56, 16, v24
	v_and_b32_e32 v57, 0xffff0000, v24
	v_lshlrev_b32_e32 v58, 16, v25
	v_and_b32_e32 v59, 0xffff0000, v25
	v_lshlrev_b32_e32 v52, 16, v28
	v_and_b32_e32 v53, 0xffff0000, v28
	v_lshlrev_b32_e32 v54, 16, v29
	v_and_b32_e32 v55, 0xffff0000, v29
	v_lshlrev_b32_e32 v48, 16, v148
	v_and_b32_e32 v49, 0xffff0000, v148
	v_lshlrev_b32_e32 v50, 16, v149
	v_and_b32_e32 v51, 0xffff0000, v149
	s_cbranch_vccnz .LBB0_1073

.LBB0_1319:
	s_load_dwordx2 s[6:7], s[0:1], 0x108
	s_cmpk_gt_i32 s14, 0x1fff
	v_lshlrev_b32_e32 v32, 2, v162
	v_mbcnt_lo_u32_b32 v33, -1, 0
	s_cbranch_scc1 .LBB0_1326
	s_load_dwordx4 s[8:11], s[0:1], 0x110
	v_lshlrev_b32_e32 v0, 3, v162
	v_mbcnt_hi_u32_b32 v21, -1, v33
	v_and_b32_e32 v23, 64, v21
	s_waitcnt vmcnt(15)
	v_mov_b32_e32 v1, 0
	s_waitcnt lgkmcnt(0)
	s_add_u32 s4, s10, 0x16c00000
	s_addc_u32 s5, s11, 0
	s_ashr_i32 s15, s14, 31
	s_lshl_b64 s[10:11], s[14:15], 12
	s_add_u32 s10, s4, s10
	s_addc_u32 s11, s5, s11
	global_load_dwordx2 v[2:3], v0, s[10:11]
	global_load_dwordx2 v[4:5], v0, s[10:11] offset:512
	global_load_dwordx2 v[6:7], v0, s[10:11] offset:1024
	global_load_dwordx2 v[8:9], v0, s[10:11] offset:1536
	global_load_dwordx2 v[10:11], v0, s[10:11] offset:2048
	global_load_dwordx2 v[12:13], v0, s[10:11] offset:2560
	global_load_dwordx2 v[14:15], v0, s[10:11] offset:3072
	global_load_dwordx2 v[16:17], v0, s[10:11] offset:3584
	v_xor_b32_e32 v28, 1, v21
	v_add_u32_e32 v23, 64, v23
	v_lshlrev_b32_e32 v18, 4, v162
	v_xor_b32_e32 v29, 2, v21
	v_mov_b32_e32 v19, v1
	v_cmp_lt_i32_e32 vcc, v28, v23
	s_lshl_b32 s10, s2, 10
	v_lshl_add_u64 v[44:45], s[4:5], 0, v[0:1]
	s_and_b32 s4, s2, 1
	v_or_b32_e32 v20, 0x400, v32
	v_xor_b32_e32 v30, 4, v21
	v_lshl_add_u64 v[34:35], s[6:7], 0, v[18:19]
	v_cndmask_b32_e32 v18, v21, v28, vcc
	v_cmp_lt_i32_e32 vcc, v29, v23
	s_and_b32 s10, s10, 0x1800
	s_lshl_b32 s4, s4, 10
	s_lshl_b32 s5, s2, 2
	v_xor_b32_e32 v31, 8, v21
	v_lshlrev_b32_e32 v24, 2, v20
	v_mov_b32_e32 v25, v1
	v_cndmask_b32_e32 v19, v21, v29, vcc
	v_cmp_lt_i32_e32 vcc, v30, v23
	s_or_b32 s4, s10, s4
	s_andn2_b32 s5, s5, 31
	v_or_b32_e32 v22, 0x500, v32
	v_xor_b32_e32 v40, 16, v21
	v_lshl_add_u64 v[36:37], s[6:7], 0, v[24:25]
	v_cndmask_b32_e32 v24, v21, v30, vcc
	v_cmp_lt_i32_e32 vcc, v31, v23
	s_lshl_b32 s11, s3, 2
	s_add_i32 s4, s4, s5
	v_xor_b32_e32 v41, 32, v21
	v_lshlrev_b32_e32 v26, 2, v22
	v_mov_b32_e32 v27, v1
	v_cndmask_b32_e32 v25, v21, v31, vcc
	v_cmp_lt_i32_e32 vcc, v40, v23
	s_or_b32 s4, s4, s11
	v_lshl_add_u64 v[38:39], s[6:7], 0, v[26:27]
	v_cndmask_b32_e32 v26, v21, v40, vcc
	v_cmp_lt_i32_e32 vcc, v41, v23
	s_or_b32 s19, s4, 1
	s_or_b32 s4, s3, 8
	v_cndmask_b32_e32 v21, v21, v41, vcc
	s_mul_i32 s4, s20, s4
	s_mov_b32 s18, 0
	v_lshlrev_b32_e32 v78, 2, v18
	v_lshlrev_b32_e32 v79, 2, v19
	v_lshlrev_b32_e32 v80, 2, v24
	v_lshlrev_b32_e32 v81, 2, v25
	v_lshlrev_b32_e32 v82, 2, v26
	v_lshlrev_b32_e32 v83, 2, v21
	s_add_i32 s21, s2, s4
	v_mov_b32_e32 v0, v1
	v_mov_b32_e32 v84, 0x358637bd
	s_mov_b32 s23, 0xf800000
	v_mov_b32_e32 v85, 0x260
	v_lshlrev_b32_e32 v86, 2, v32
	v_lshlrev_b32_e32 v87, 2, v20
	v_lshlrev_b32_e32 v88, 2, v22
	v_mov_b32_e32 v18, v1
	v_mov_b32_e32 v19, v1
	v_mov_b32_e32 v20, v1
	v_mov_b32_e32 v21, v1
	v_mov_b32_e32 v22, v1
	v_mov_b32_e32 v23, v1
	v_mov_b32_e32 v24, v1
	v_mov_b32_e32 v25, v1
	v_mov_b32_e32 v26, v1
	v_mov_b32_e32 v28, v1
	v_mov_b32_e32 v29, v1
	v_mov_b32_e32 v30, v1
	v_mov_b32_e32 v31, v1
	s_waitcnt vmcnt(7)
	v_lshlrev_b32_e32 v74, 16, v2
	v_and_b32_e32 v75, 0xffff0000, v2
	s_waitcnt vmcnt(5)
	v_lshlrev_b32_e32 v66, 16, v6
	v_and_b32_e32 v67, 0xffff0000, v6
	v_or_b32_e32 v6, 0x600, v32
	v_lshlrev_b32_e32 v76, 16, v3
	v_and_b32_e32 v77, 0xffff0000, v3
	s_waitcnt vmcnt(4)
	v_lshlrev_b32_e32 v62, 16, v8
	v_and_b32_e32 v63, 0xffff0000, v8
	v_lshlrev_b32_e32 v2, 2, v6
	v_mov_b32_e32 v3, v1
	v_or_b32_e32 v8, 0x700, v32
	v_lshl_add_u64 v[40:41], s[6:7], 0, v[2:3]
	v_lshlrev_b32_e32 v2, 2, v8
	v_lshlrev_b32_e32 v70, 16, v4
	v_and_b32_e32 v71, 0xffff0000, v4
	v_lshlrev_b32_e32 v72, 16, v5
	v_and_b32_e32 v73, 0xffff0000, v5
	v_lshlrev_b32_e32 v68, 16, v7
	v_and_b32_e32 v69, 0xffff0000, v7
	v_lshlrev_b32_e32 v64, 16, v9
	v_and_b32_e32 v65, 0xffff0000, v9
	s_waitcnt vmcnt(3)
	v_lshlrev_b32_e32 v58, 16, v10
	v_and_b32_e32 v59, 0xffff0000, v10
	v_lshlrev_b32_e32 v60, 16, v11
	v_and_b32_e32 v61, 0xffff0000, v11
	s_waitcnt vmcnt(2)
	v_lshlrev_b32_e32 v54, 16, v12
	v_and_b32_e32 v55, 0xffff0000, v12
	v_lshlrev_b32_e32 v56, 16, v13
	v_and_b32_e32 v57, 0xffff0000, v13
	s_waitcnt vmcnt(1)
	v_lshlrev_b32_e32 v50, 16, v14
	v_and_b32_e32 v51, 0xffff0000, v14
	v_lshlrev_b32_e32 v52, 16, v15
	v_and_b32_e32 v53, 0xffff0000, v15
	s_waitcnt vmcnt(0)
	v_lshlrev_b32_e32 v46, 16, v16
	v_and_b32_e32 v47, 0xffff0000, v16
	v_lshlrev_b32_e32 v48, 16, v17
	v_and_b32_e32 v49, 0xffff0000, v17
	v_lshl_add_u64 v[42:43], s[6:7], 0, v[2:3]
	v_mov_b32_e32 v2, v1
	v_mov_b32_e32 v4, v1
	v_mov_b32_e32 v5, v1
	v_lshlrev_b32_e32 v89, 2, v6
	v_lshlrev_b32_e32 v90, 2, v8
	v_mov_b32_e32 v6, v1
	v_mov_b32_e32 v7, v1
	v_mov_b32_e32 v8, v1
	v_mov_b32_e32 v9, v1
	v_mov_b32_e32 v10, v1
	v_mov_b32_e32 v11, v1
	v_mov_b32_e32 v12, v1
	v_mov_b32_e32 v13, v1
	v_mov_b32_e32 v14, v1
	v_mov_b32_e32 v15, v1
	v_mov_b32_e32 v16, v1
	v_mov_b32_e32 v17, v1
	s_mov_b32 s98, -1
	s_branch .LBB0_1322
.LBB0_1321:
	s_mov_b32 s99, 0
	s_cmp_eq_u32 s99, s98
	s_cbranch_scc1 .Lnorm_skip_1321
	s_mov_b32 s98, s99
	global_load_dwordx4 v[116:119], v[34:35], off
	global_load_dwordx4 v[120:123], v[34:35], off offset:1024
	global_load_dwordx4 v[124:127], v[34:35], off offset:2048
	global_load_dwordx4 v[128:131], v[34:35], off offset:3072
	global_load_dwordx4 v[132:135], v[36:37], off
	global_load_dwordx4 v[136:139], v[38:39], off
	global_load_dwordx4 v[140:143], v[40:41], off
	global_load_dwordx4 v[144:147], v[42:43], off
.Lnorm_skip_1321:
	v_mov_b32_e32 v94, v71
	v_mov_b32_e32 v95, v75
	v_mov_b32_e32 v92, v70
	v_mov_b32_e32 v93, v74
	v_pk_mul_f32 v[94:95], v[94:95], v[94:95]
	v_mov_b32_e32 v96, v73
	v_mov_b32_e32 v97, v77
	v_pk_fma_f32 v[92:93], v[92:93], v[92:93], v[94:95]
	v_mov_b32_e32 v94, v72
	v_mov_b32_e32 v95, v76
	v_pk_mul_f32 v[96:97], v[96:97], v[96:97]
	s_ashr_i32 s15, s14, 31
	v_pk_fma_f32 v[94:95], v[94:95], v[94:95], v[96:97]
	v_pk_mul_f32 v[96:97], v[66:67], v[66:67]
	v_pk_add_f32 v[92:93], v[92:93], v[94:95]
	v_pk_mul_f32 v[94:95], v[68:69], v[68:69]
	v_pk_add_f32 v[92:93], v[92:93], v[92:93] op_sel_hi:[0,1]
	v_pk_mov_b32 v[98:99], v[96:97], v[94:95] op_sel:[1,0]
	v_mov_b32_e32 v97, v95
	v_pk_add_f32 v[94:95], v[98:99], v[96:97]
	v_mul_f32_e32 v96, v62, v62
	v_pk_fma_f32 v[96:97], v[62:63], v[62:63], v[96:97] op_sel_hi:[1,1,0]
	v_pk_add_f32 v[94:95], v[94:95], v[94:95] op_sel_hi:[0,1]
	v_mul_f32_e32 v96, v64, v64
	v_pk_fma_f32 v[98:99], v[64:65], v[64:65], v[96:97] op_sel_hi:[1,1,0]
	v_mul_f32_e32 v96, v58, v58
	v_mul_f32_e32 v98, v59, v59
	v_mul_f32_e32 v94, v60, v60
	v_mul_f32_e32 v92, v61, v61
	v_pk_add_f32 v[96:97], v[96:97], v[98:99]
	v_pk_add_f32 v[92:93], v[94:95], v[92:93]
	v_pk_mul_f32 v[94:95], v[56:57], v[56:57]
	v_pk_add_f32 v[92:93], v[96:97], v[92:93]
	v_pk_mul_f32 v[96:97], v[54:55], v[54:55]
	v_pk_add_f32 v[92:93], v[92:93], v[92:93] op_sel_hi:[0,1]
	v_pk_mov_b32 v[98:99], v[96:97], v[94:95] op_sel:[1,0]
	v_mov_b32_e32 v97, v95
	v_pk_add_f32 v[94:95], v[98:99], v[96:97]
	v_mul_f32_e32 v96, v50, v50
	v_pk_fma_f32 v[96:97], v[50:51], v[50:51], v[96:97] op_sel_hi:[1,1,0]
	v_pk_add_f32 v[94:95], v[94:95], v[94:95] op_sel_hi:[0,1]
	v_mul_f32_e32 v96, v52, v52
	v_pk_fma_f32 v[98:99], v[52:53], v[52:53], v[96:97] op_sel_hi:[1,1,0]
	v_mul_f32_e32 v96, v46, v46
	v_mul_f32_e32 v98, v47, v47
	v_mul_f32_e32 v94, v48, v48
	v_mul_f32_e32 v92, v49, v49
	v_pk_add_f32 v[96:97], v[96:97], v[98:99]
	v_pk_add_f32 v[92:93], v[94:95], v[92:93]
	s_nop 0
	v_pk_add_f32 v[92:93], v[96:97], v[92:93]
	s_nop 0
	v_add_f32_e32 v91, v92, v93
	ds_bpermute_b32 v92, v78, v91
	s_waitcnt lgkmcnt(0)
	v_add_f32_e32 v91, v91, v92
	ds_bpermute_b32 v92, v79, v91
	s_waitcnt lgkmcnt(0)
	v_add_f32_e32 v91, v91, v92
	ds_bpermute_b32 v92, v80, v91
	s_waitcnt lgkmcnt(0)
	v_add_f32_e32 v91, v91, v92
	ds_bpermute_b32 v92, v81, v91
	s_waitcnt lgkmcnt(0)
	v_add_f32_e32 v91, v91, v92
	ds_bpermute_b32 v92, v82, v91
	s_waitcnt lgkmcnt(0)
	v_add_f32_e32 v91, v91, v92
	ds_bpermute_b32 v92, v83, v91
	s_waitcnt lgkmcnt(0)
	v_add_f32_e32 v91, v91, v92
	v_fmamk_f32 v91, v91, 0x3a000000, v84
	v_mul_f32_e32 v92, 0x4f800000, v91
	v_cmp_gt_f32_e32 vcc, s23, v91
	s_nop 1
	v_cndmask_b32_e32 v91, v91, v92, vcc
	v_sqrt_f32_e32 v92, v91
	s_nop 0
	v_add_u32_e32 v93, -1, v92
	v_fma_f32 v94, -v93, v92, v91
	v_cmp_ge_f32_e64 s[4:5], 0, v94
	v_add_u32_e32 v94, 1, v92
	s_nop 0
	v_cndmask_b32_e64 v93, v92, v93, s[4:5]
	v_fma_f32 v92, -v94, v92, v91
	v_cmp_lt_f32_e64 s[4:5], 0, v92
	s_nop 1
	v_cndmask_b32_e64 v92, v93, v94, s[4:5]
	v_mul_f32_e32 v93, 0x37800000, v92
	v_cndmask_b32_e32 v92, v92, v93, vcc
	v_cmp_class_f32_e32 vcc, v91, v85
	s_nop 1
	v_cndmask_b32_e32 v91, v92, v91, vcc
	v_div_scale_f32 v92, s[4:5], v91, v91, 1.0
	v_rcp_f32_e32 v93, v92
	s_lshl_b64 s[4:5], s[14:15], 13
	s_add_u32 s4, s8, s4
	s_addc_u32 s5, s9, s5
	v_fma_f32 v94, -v92, v93, 1.0
	v_fmac_f32_e32 v93, v94, v93
	v_div_scale_f32 v94, vcc, 1.0, v91, 1.0
	v_mul_f32_e32 v95, v94, v93
	v_fma_f32 v96, -v92, v95, v94
	v_fmac_f32_e32 v95, v96, v93
	v_fma_f32 v92, -v92, v95, v94
	v_div_fmas_f32 v92, v92, v93, v95
	v_div_fixup_f32 v92, v92, v91, 1.0
	v_pk_mul_f32 v[94:95], v[74:75], v[92:93] op_sel_hi:[1,0]
	v_pk_mul_f32 v[96:97], v[76:77], v[92:93] op_sel_hi:[1,0]
	s_waitcnt vmcnt(0)
	v_mov_b64_e32 v[74:75], v[116:117]
	v_mov_b64_e32 v[76:77], v[118:119]
	s_mov_b32 s14, s10
	s_add_i32 s21, s21, s22
	s_add_i32 s18, s18, 1
	s_and_b64 vcc, exec, s[16:17]
	s_waitcnt vmcnt(0)
	v_pk_mul_f32 v[76:77], v[76:77], v[96:97]
	v_pk_mul_f32 v[74:75], v[74:75], v[94:95]
	global_store_dwordx4 v86, v[74:77], s[4:5] nt
	s_nop 1
	v_pk_mul_f32 v[74:75], v[72:73], v[92:93] op_sel_hi:[1,0]
	v_pk_mul_f32 v[76:77], v[70:71], v[92:93] op_sel_hi:[1,0]
	v_mov_b64_e32 v[70:71], v[120:121]
	v_mov_b64_e32 v[72:73], v[122:123]
	v_pk_mul_f32 v[70:71], v[70:71], v[76:77]
	v_pk_mul_f32 v[72:73], v[72:73], v[74:75]
	global_store_dwordx4 v86, v[70:73], s[4:5] offset:1024 nt
	v_mov_b32_e32 v74, v0
	v_mov_b32_e32 v75, v1
	v_pk_mul_f32 v[70:71], v[68:69], v[92:93] op_sel_hi:[1,0]
	v_pk_mul_f32 v[72:73], v[66:67], v[92:93] op_sel_hi:[1,0]
	v_mov_b64_e32 v[66:67], v[124:125]
	v_mov_b64_e32 v[68:69], v[126:127]
	v_mov_b32_e32 v76, v2
	v_mov_b32_e32 v77, v3
	v_pk_mul_f32 v[66:67], v[66:67], v[72:73]
	v_pk_mul_f32 v[68:69], v[68:69], v[70:71]
	global_store_dwordx4 v86, v[66:69], s[4:5] offset:2048 nt
	v_mov_b32_e32 v70, v4
	v_mov_b32_e32 v71, v5
	v_pk_mul_f32 v[66:67], v[64:65], v[92:93] op_sel_hi:[1,0]
	v_pk_mul_f32 v[68:69], v[62:63], v[92:93] op_sel_hi:[1,0]
	v_mov_b64_e32 v[62:63], v[128:129]
	v_mov_b64_e32 v[64:65], v[130:131]
	v_mov_b32_e32 v72, v6
	v_mov_b32_e32 v73, v7
	v_pk_mul_f32 v[62:63], v[62:63], v[68:69]
	v_pk_mul_f32 v[64:65], v[64:65], v[66:67]
	global_store_dwordx4 v86, v[62:65], s[4:5] offset:3072 nt
	v_mov_b32_e32 v66, v8
	v_mov_b32_e32 v67, v9
	v_pk_mul_f32 v[62:63], v[60:61], v[92:93] op_sel_hi:[1,0]
	v_pk_mul_f32 v[64:65], v[58:59], v[92:93] op_sel_hi:[1,0]
	v_mov_b64_e32 v[58:59], v[132:133]
	v_mov_b64_e32 v[60:61], v[134:135]
	v_mov_b32_e32 v68, v10
	v_mov_b32_e32 v69, v11
	v_pk_mul_f32 v[58:59], v[64:65], v[58:59]
	v_pk_mul_f32 v[60:61], v[62:63], v[60:61]
	global_store_dwordx4 v87, v[58:61], s[4:5] nt
	v_mov_b32_e32 v62, v12
	v_mov_b32_e32 v63, v13
	v_pk_mul_f32 v[58:59], v[56:57], v[92:93] op_sel_hi:[1,0]
	v_pk_mul_f32 v[60:61], v[54:55], v[92:93] op_sel_hi:[1,0]
	v_mov_b64_e32 v[54:55], v[136:137]
	v_mov_b64_e32 v[56:57], v[138:139]
	v_mov_b32_e32 v64, v14
	v_mov_b32_e32 v65, v15
	v_pk_mul_f32 v[54:55], v[60:61], v[54:55]
	v_pk_mul_f32 v[56:57], v[58:59], v[56:57]
	global_store_dwordx4 v88, v[54:57], s[4:5] nt
	v_mov_b32_e32 v58, v16
	v_mov_b32_e32 v59, v17
	v_pk_mul_f32 v[54:55], v[52:53], v[92:93] op_sel_hi:[1,0]
	v_pk_mul_f32 v[56:57], v[50:51], v[92:93] op_sel_hi:[1,0]
	v_mov_b64_e32 v[50:51], v[140:141]
	v_mov_b64_e32 v[52:53], v[142:143]
	v_mov_b32_e32 v60, v18
	v_mov_b32_e32 v61, v19
	v_pk_mul_f32 v[50:51], v[56:57], v[50:51]
	v_pk_mul_f32 v[52:53], v[54:55], v[52:53]
	global_store_dwordx4 v89, v[50:53], s[4:5] nt
	v_mov_b32_e32 v54, v20
	v_mov_b32_e32 v55, v21
	v_pk_mul_f32 v[50:51], v[48:49], v[92:93] op_sel_hi:[1,0]
	v_pk_mul_f32 v[52:53], v[46:47], v[92:93] op_sel_hi:[1,0]
	v_mov_b64_e32 v[46:47], v[144:145]
	v_mov_b64_e32 v[48:49], v[146:147]
	v_mov_b32_e32 v56, v22
	v_mov_b32_e32 v57, v23
	v_pk_mul_f32 v[46:47], v[52:53], v[46:47]
	v_pk_mul_f32 v[48:49], v[50:51], v[48:49]
	global_store_dwordx4 v90, v[46:49], s[4:5] nt
	v_mov_b32_e32 v50, v24
	v_mov_b32_e32 v51, v25
	v_mov_b32_e32 v46, v28
	v_mov_b32_e32 v47, v29
	v_mov_b32_e32 v48, v30
	v_mov_b32_e32 v49, v31
	v_mov_b32_e32 v52, v26
	v_mov_b32_e32 v53, v27
	s_cbranch_vccnz .LBB0_1326

	.amdhsa_kernel _Z10fwd_kernelILb1EEv6Params
		.amdhsa_group_segment_fixed_size 0
		.amdhsa_private_segment_fixed_size 0
		.amdhsa_kernarg_size 552
		.amdhsa_user_sgpr_count 2
		.amdhsa_user_sgpr_dispatch_ptr 0
		.amdhsa_user_sgpr_queue_ptr 0
		.amdhsa_user_sgpr_kernarg_segment_ptr 1
		.amdhsa_user_sgpr_dispatch_id 0
		.amdhsa_user_sgpr_kernarg_preload_length 0
		.amdhsa_user_sgpr_kernarg_preload_offset 0
		.amdhsa_user_sgpr_private_segment_size 0
		.amdhsa_uses_dynamic_stack 0
		.amdhsa_enable_private_segment 0
		.amdhsa_system_sgpr_workgroup_id_x 1
		.amdhsa_system_sgpr_workgroup_id_y 0
		.amdhsa_system_sgpr_workgroup_id_z 0
		.amdhsa_system_sgpr_workgroup_info 0
		.amdhsa_system_vgpr_workitem_id 0
		.amdhsa_next_free_vgpr 256
		.amdhsa_next_free_sgpr 102
		.amdhsa_accum_offset 256
		.amdhsa_reserve_vcc 1
		.amdhsa_float_round_mode_32 0
		.amdhsa_float_round_mode_16_64 0
		.amdhsa_float_denorm_mode_32 3
		.amdhsa_float_denorm_mode_16_64 3
		.amdhsa_dx10_clamp 1
		.amdhsa_ieee_mode 1
		.amdhsa_fp16_overflow 0
		.amdhsa_tg_split 0
		.amdhsa_exception_fp_ieee_invalid_op 0
		.amdhsa_exception_fp_denorm_src 0
		.amdhsa_exception_fp_ieee_div_zero 0
		.amdhsa_exception_fp_ieee_overflow 0
		.amdhsa_exception_fp_ieee_underflow 0
		.amdhsa_exception_fp_ieee_inexact 0
		.amdhsa_exception_int_div_zero 0
	.end_amdhsa_kernel

	.amdhsa_kernel _Z10fwd_kernelILb0EEv6Params
		.amdhsa_group_segment_fixed_size 0
		.amdhsa_private_segment_fixed_size 0
		.amdhsa_kernarg_size 552
		.amdhsa_user_sgpr_count 2
		.amdhsa_user_sgpr_dispatch_ptr 0
		.amdhsa_user_sgpr_queue_ptr 0
		.amdhsa_user_sgpr_kernarg_segment_ptr 1
		.amdhsa_user_sgpr_dispatch_id 0
		.amdhsa_user_sgpr_kernarg_preload_length 0
		.amdhsa_user_sgpr_kernarg_preload_offset 0
		.amdhsa_user_sgpr_private_segment_size 0
		.amdhsa_uses_dynamic_stack 0
		.amdhsa_enable_private_segment 0
		.amdhsa_system_sgpr_workgroup_id_x 1
		.amdhsa_system_sgpr_workgroup_id_y 0
		.amdhsa_system_sgpr_workgroup_id_z 0
		.amdhsa_system_sgpr_workgroup_info 0
		.amdhsa_system_vgpr_workitem_id 0
		.amdhsa_next_free_vgpr 231
		.amdhsa_next_free_sgpr 102
		.amdhsa_accum_offset 232
		.amdhsa_reserve_vcc 1
		.amdhsa_float_round_mode_32 0
		.amdhsa_float_round_mode_16_64 0
		.amdhsa_float_denorm_mode_32 3
		.amdhsa_float_denorm_mode_16_64 3
		.amdhsa_dx10_clamp 1
		.amdhsa_ieee_mode 1
		.amdhsa_fp16_overflow 0
		.amdhsa_tg_split 0
		.amdhsa_exception_fp_ieee_invalid_op 0
		.amdhsa_exception_fp_denorm_src 0
		.amdhsa_exception_fp_ieee_div_zero 0
		.amdhsa_exception_fp_ieee_overflow 0
		.amdhsa_exception_fp_ieee_underflow 0
		.amdhsa_exception_fp_ieee_inexact 0
		.amdhsa_exception_int_div_zero 0
	.end_amdhsa_kernel

amdhsa.kernels:
  - .agpr_count:     0
    .args:
      - .offset:         0
        .size:           296
        .value_kind:     by_value
      - .offset:         296
        .size:           4
        .value_kind:     hidden_block_count_x
      - .offset:         300
        .size:           4
        .value_kind:     hidden_block_count_y
      - .offset:         304
        .size:           4
        .value_kind:     hidden_block_count_z
      - .offset:         308
        .size:           2
        .value_kind:     hidden_group_size_x
      - .offset:         310
        .size:           2
        .value_kind:     hidden_group_size_y
      - .offset:         312
        .size:           2
        .value_kind:     hidden_group_size_z
      - .offset:         314
        .size:           2
        .value_kind:     hidden_remainder_x
      - .offset:         316
        .size:           2
        .value_kind:     hidden_remainder_y
      - .offset:         318
        .size:           2
        .value_kind:     hidden_remainder_z
      - .offset:         336
        .size:           8
        .value_kind:     hidden_global_offset_x
      - .offset:         344
        .size:           8
        .value_kind:     hidden_global_offset_y
      - .offset:         352
        .size:           8
        .value_kind:     hidden_global_offset_z
      - .offset:         360
        .size:           2
        .value_kind:     hidden_grid_dims
      - .offset:         416
        .size:           4
        .value_kind:     hidden_dynamic_lds_size
    .group_segment_fixed_size: 0
    .kernarg_segment_align: 8
    .kernarg_segment_size: 552
    .language:       OpenCL C
    .language_version:
      - 2
      - 0
    .max_flat_workgroup_size: 512
    .name:           _Z10fwd_kernelILb1EEv6Params
    .private_segment_fixed_size: 0
    .sgpr_count:     108
    .sgpr_spill_count: 55
    .symbol:         _Z10fwd_kernelILb1EEv6Params.kd
    .uniform_work_group_size: 1
    .uses_dynamic_stack: false
    .vgpr_count:     256
    .vgpr_spill_count: 0
    .wavefront_size: 64
  - .agpr_count:     0
    .args:
      - .offset:         0
        .size:           296
        .value_kind:     by_value
      - .offset:         296
        .size:           4
        .value_kind:     hidden_block_count_x
      - .offset:         300
        .size:           4
        .value_kind:     hidden_block_count_y
      - .offset:         304
        .size:           4
        .value_kind:     hidden_block_count_z
      - .offset:         308
        .size:           2
        .value_kind:     hidden_group_size_x
      - .offset:         310
        .size:           2
        .value_kind:     hidden_group_size_y
      - .offset:         312
        .size:           2
        .value_kind:     hidden_group_size_z
      - .offset:         314
        .size:           2
        .value_kind:     hidden_remainder_x
      - .offset:         316
        .size:           2
        .value_kind:     hidden_remainder_y
      - .offset:         318
        .size:           2
        .value_kind:     hidden_remainder_z
      - .offset:         336
        .size:           8
        .value_kind:     hidden_global_offset_x
      - .offset:         344
        .size:           8
        .value_kind:     hidden_global_offset_y
      - .offset:         352
        .size:           8
        .value_kind:     hidden_global_offset_z
      - .offset:         360
        .size:           2
        .value_kind:     hidden_grid_dims
      - .offset:         416
        .size:           4
        .value_kind:     hidden_dynamic_lds_size
    .group_segment_fixed_size: 0
    .kernarg_segment_align: 8
    .kernarg_segment_size: 552
    .language:       OpenCL C
    .language_version:
      - 2
      - 0
    .max_flat_workgroup_size: 512
    .name:           _Z10fwd_kernelILb0EEv6Params
    .private_segment_fixed_size: 0
    .sgpr_count:     108
    .sgpr_spill_count: 48
    .symbol:         _Z10fwd_kernelILb0EEv6Params.kd
    .uniform_work_group_size: 1
    .uses_dynamic_stack: false
    .vgpr_count:     231
    .vgpr_spill_count: 0
    .wavefront_size: 64
